# gate mini-GEMM: issue its 20 fragment loads up front (one wait) instead of 4-5 dependent load batches
# baseline (speedup 1.0000x reference)
; #define LAS __attribute__((address_space(3)))
; __device__ __forceinline__ unsigned f2bf(float f) { return pk2(f, 0.f) & 0xffffu; }
; __device__ __forceinline__ void gate_stash(LAS unsigned char* lds, const float* wg_f, const float* wg_b) {
;     int tid_o_ = threadIdx.x; asm volatile("" : "+v"(tid_o_)); const int tid = tid_o_, lane = tid & 63, wave = __builtin_amdgcn_readfirstlane(tid >> 6); (void)tid;
;         {
;             const int d = wave >> 2, lr_g = lane & 15, lq_g = lane >> 4; const float* wg = d ? wg_b : wg_f;
; #pragma unroll
;             for (int c4 = 0; c4 < 4; ++c4) { const int colc = 16 * (4 * (wave & 3) + c4) + lr_g; bf16x8 b1, b2;
; #pragma unroll
;                 for (int e = 0; e < 8; ++e) { const float wv = wg[(((8 * lq_g) & 15) + e) * 256 + colc]; const unsigned hi = f2bf(wv); const float rem = wv - __builtin_bit_cast(float, hi << 16);
;                     b1[e] = (short)hi; b2[e] = (lq_g < 2) ? (short)f2bf(rem) : (short)0; }
;                 *(LAS bf16x8*)(lds + 65536 + ((wave * 8 + c4 * 2) * 64 + lane) * 16) = b1; *(LAS bf16x8*)(lds + 65536 + ((wave * 8 + c4 * 2 + 1) * 64 + lane) * 16) = b2; }
.LBB0_111:
	v_mov_b32_e32 v1, v0
	s_waitcnt vmcnt(0)
	s_barrier
	s_nop 0
	v_readfirstlane_b32 s0, v1
	s_cmpk_lt_u32 s0, 0x100
	s_waitcnt vmcnt(3)
	v_lshlrev_b32_e32 v3, 7, v1
	v_and_b32_e32 v2, 15, v1
	s_cselect_b32 s5, s63, s67
	s_cselect_b32 s4, s62, s66
	s_and_b32 s1, s0, 0xc0
	v_and_b32_e32 v3, 0x800, v3
	v_or3_b32 v2, s1, v2, v3
	v_lshlrev_b32_e32 v2, 2, v2
	s_waitcnt vmcnt(2)
	v_or_b32_e32 v8, 0x1000, v2
	s_waitcnt vmcnt(1)
	v_or_b32_e32 v10, 0x1400, v2
	global_load_dword v4, v2, s[4:5]
	global_load_dword v5, v2, s[4:5] offset:1024
	global_load_dword v6, v2, s[4:5] offset:2048
	global_load_dword v7, v2, s[4:5] offset:3072
	global_load_dword v9, v8, s[4:5]
	v_or_b32_e32 v11, 0x1800, v2
	global_load_dword v12, v10, s[4:5]
	global_load_dword v13, v11, s[4:5]
	s_waitcnt vmcnt(7)
	v_or_b32_e32 v14, 0x1c00, v2
	global_load_dword v15, v14, s[4:5]
	v_or_b32_e32 v17, 0x400, v2
	global_load_dword v18, v17, s[4:5] offset:64
	global_load_dword v16, v2, s[4:5] offset:64
	v_or_b32_e32 v20, 0x800, v2
	v_or_b32_e32 v21, 0xc00, v2
	global_load_dword v22, v20, s[4:5] offset:64
	global_load_dword v23, v21, s[4:5] offset:64
	global_load_dword v24, v17, s[4:5] offset:128
	global_load_dword v25, v2, s[4:5] offset:128
	s_nop 0
	global_load_dword v2, v2, s[4:5] offset:192
	s_nop 0
	global_load_dword v26, v8, s[4:5] offset:64
	global_load_dword v27, v10, s[4:5] offset:64
	global_load_dword v28, v8, s[4:5] offset:128
	global_load_dword v29, v10, s[4:5] offset:128
	global_load_dword v30, v10, s[4:5] offset:192
	global_load_dword v31, v8, s[4:5] offset:192
	global_load_dword v32, v11, s[4:5] offset:64
	global_load_dword v33, v14, s[4:5] offset:64
	global_load_dword v34, v11, s[4:5] offset:128
	global_load_dword v35, v14, s[4:5] offset:128
	s_nop 0
	global_load_dword v14, v14, s[4:5] offset:192
	s_nop 0
	global_load_dword v36, v11, s[4:5] offset:192
	s_lshl_b32 s0, s0, 7
	s_add_i32 s33, 0, 0x10000
	s_and_b32 s0, s0, 0xffffe000
	v_and_b32_e32 v1, 63, v1
	s_add_i32 s0, s33, s0
	global_load_dword v45, v20, s[4:5] offset:128
	v_cmp_gt_u32_e32 vcc, 32, v1
	v_lshl_add_u32 v19, v1, 4, s0
	v_mov_b32_e32 v3, 0
	s_waitcnt vmcnt(27)
	v_cvt_pk_bf16_f32 v8, v4, 0
	s_waitcnt vmcnt(26)
	v_cvt_pk_bf16_f32 v10, v5, 0
	s_waitcnt vmcnt(25)
	v_cvt_pk_bf16_f32 v11, v6, 0
	s_waitcnt vmcnt(24)
	v_cvt_pk_bf16_f32 v37, v7, 0
	v_lshlrev_b32_e32 v38, 16, v8
	v_lshlrev_b32_e32 v39, 16, v10
	v_lshlrev_b32_e32 v40, 16, v11
	s_waitcnt vmcnt(23)
	v_cvt_pk_bf16_f32 v42, v9, 0
	s_waitcnt vmcnt(22)
	v_cvt_pk_bf16_f32 v43, v12, 0
	s_waitcnt vmcnt(21)
	v_cvt_pk_bf16_f32 v44, v13, 0
	v_lshlrev_b32_e32 v41, 16, v37
	v_sub_f32_e32 v4, v4, v38
	v_sub_f32_e32 v5, v5, v39
	v_sub_f32_e32 v6, v6, v40
	v_lshlrev_b32_e32 v38, 16, v42
	v_lshlrev_b32_e32 v39, 16, v43
	v_lshlrev_b32_e32 v40, 16, v44
	v_sub_f32_e32 v7, v7, v41
	v_cvt_pk_bf16_f32 v4, v4, s0
	v_cvt_pk_bf16_f32 v5, v5, s0
	v_cvt_pk_bf16_f32 v6, v6, s0
	v_sub_f32_e32 v9, v9, v38
	v_sub_f32_e32 v12, v12, v39
	v_sub_f32_e32 v13, v13, v40
	v_cvt_pk_bf16_f32 v7, v7, s0
	v_cndmask_b32_e32 v1, 0, v4, vcc
	v_cndmask_b32_e32 v38, 0, v5, vcc
	v_cndmask_b32_e32 v39, 0, v6, vcc
	v_cvt_pk_bf16_f32 v4, v9, s0
	v_cvt_pk_bf16_f32 v5, v12, s0
	v_cvt_pk_bf16_f32 v6, v13, s0
	s_mov_b32 s0, 0x5040100
	v_cndmask_b32_e32 v13, 0, v5, vcc
	v_perm_b32 v5, v37, v11, s0
	global_load_dword v37, v21, s[4:5] offset:128
	s_waitcnt vmcnt(21)
	v_cvt_pk_bf16_f32 v9, v15, 0
	v_cndmask_b32_e32 v12, 0, v4, vcc
	v_perm_b32 v4, v10, v8, s0
	v_lshlrev_b32_e32 v8, 16, v9
	v_sub_f32_e32 v8, v15, v8
	v_cvt_pk_bf16_f32 v8, v8, s0
	v_cndmask_b32_e32 v40, 0, v7, vcc
	v_cndmask_b32_e32 v41, 0, v6, vcc
	v_perm_b32 v7, v9, v44, s0
	v_perm_b32 v6, v43, v42, s0
	v_cndmask_b32_e32 v10, 0, v8, vcc
	v_perm_b32 v8, v38, v1, s0
	s_waitcnt vmcnt(19)
	v_cvt_pk_bf16_f32 v1, v16, 0
	v_perm_b32 v9, v40, v39, s0
	v_perm_b32 v11, v10, v41, s0
	v_perm_b32 v10, v13, v12, s0
	ds_write_b128 v19, v[4:7]
	ds_write_b128 v19, v[8:11] offset:1024
	v_lshlrev_b32_e32 v4, 16, v1
	v_sub_f32_e32 v4, v16, v4
	global_load_dword v13, v21, s[4:5] offset:192
	global_load_dword v15, v20, s[4:5] offset:192
	global_load_dword v16, v17, s[4:5] offset:192
	v_cvt_pk_bf16_f32 v4, v4, s0
	v_cndmask_b32_e32 v8, 0, v4, vcc
	v_cvt_pk_bf16_f32 v4, v18, 0
	v_lshlrev_b32_e32 v5, 16, v4
	v_sub_f32_e32 v5, v18, v5
	v_cvt_pk_bf16_f32 v5, v5, s0
	v_cndmask_b32_e32 v12, 0, v5, vcc
	s_waitcnt vmcnt(21)
	v_cvt_pk_bf16_f32 v5, v22, 0
	v_lshlrev_b32_e32 v6, 16, v5
	v_sub_f32_e32 v6, v22, v6
	v_cvt_pk_bf16_f32 v6, v6, s0
	s_waitcnt vmcnt(20)
	v_cvt_pk_bf16_f32 v10, v23, 0
	v_cndmask_b32_e32 v9, 0, v6, vcc
	v_lshlrev_b32_e32 v6, 16, v10
	v_sub_f32_e32 v6, v23, v6
	v_cvt_pk_bf16_f32 v6, v6, s0
	v_cndmask_b32_e32 v17, 0, v6, vcc
	s_waitcnt vmcnt(16)
	v_cvt_pk_bf16_f32 v6, v26, 0
	v_lshlrev_b32_e32 v7, 16, v6
	v_sub_f32_e32 v7, v26, v7
	v_cvt_pk_bf16_f32 v7, v7, s0
	s_waitcnt vmcnt(15)
	v_cvt_pk_bf16_f32 v11, v27, 0
	v_cndmask_b32_e32 v18, 0, v7, vcc
	v_lshlrev_b32_e32 v7, 16, v11
	v_sub_f32_e32 v7, v27, v7
	v_cvt_pk_bf16_f32 v7, v7, s0
	v_cndmask_b32_e32 v20, 0, v7, vcc
	s_waitcnt vmcnt(10)
	v_cvt_pk_bf16_f32 v7, v32, 0
	s_waitcnt vmcnt(9)
	v_cvt_pk_bf16_f32 v22, v33, 0
	v_lshlrev_b32_e32 v21, 16, v7
	v_perm_b32 v4, v4, v1, s0
	v_lshlrev_b32_e32 v1, 16, v22
	v_sub_f32_e32 v21, v32, v21
	v_sub_f32_e32 v1, v33, v1
	v_cvt_pk_bf16_f32 v21, v21, s0
	v_cvt_pk_bf16_f32 v1, v1, s0
	v_cndmask_b32_e32 v21, 0, v21, vcc
	v_cndmask_b32_e32 v1, 0, v1, vcc
	v_perm_b32 v7, v22, v7, s0
	v_perm_b32 v6, v11, v6, s0
	v_perm_b32 v5, v10, v5, s0
	v_perm_b32 v11, v1, v21, s0
	v_cvt_pk_bf16_f32 v1, v25, 0
	v_perm_b32 v10, v20, v18, s0
	v_perm_b32 v9, v17, v9, s0
	v_perm_b32 v8, v12, v8, s0
	ds_write_b128 v19, v[4:7] offset:2048
	ds_write_b128 v19, v[8:11] offset:3072
	v_lshlrev_b32_e32 v4, 16, v1
	v_sub_f32_e32 v4, v25, v4
	v_cvt_pk_bf16_f32 v4, v4, s0
	v_cndmask_b32_e32 v8, 0, v4, vcc
	v_cvt_pk_bf16_f32 v4, v24, 0
	v_lshlrev_b32_e32 v5, 16, v4
	v_sub_f32_e32 v5, v24, v5
	v_cvt_pk_bf16_f32 v5, v5, s0
	v_cndmask_b32_e32 v12, 0, v5, vcc
	s_waitcnt vmcnt(4)
; #define LAS __attribute__((address_space(3)))
; __device__ __forceinline__ unsigned f2bf(float f) { return pk2(f, 0.f) & 0xffffu; }
; __device__ __forceinline__ void gate_stash(LAS unsigned char* lds, const float* wg_f, const float* wg_b) {
;     ...
;             for (int c4 = 0; c4 < 4; ++c4) { const int colc = 16 * (4 * (wave & 3) + c4) + lr_g; bf16x8 b1, b2;
; #pragma unroll
;                 for (int e = 0; e < 8; ++e) { const float wv = wg[(((8 * lq_g) & 15) + e) * 256 + colc]; const unsigned hi = f2bf(wv); const float rem = wv - __builtin_bit_cast(float, hi << 16);
;                     b1[e] = (short)hi; b2[e] = (lq_g < 2) ? (short)f2bf(rem) : (short)0; }
;                 *(LAS bf16x8*)(lds + 65536 + ((wave * 8 + c4 * 2) * 64 + lane) * 16) = b1; *(LAS bf16x8*)(lds + 65536 + ((wave * 8 + c4 * 2 + 1) * 64 + lane) * 16) = b2; }
;         }
; }
; __device__ __forceinline__ void gate_half_item(LAS unsigned char* lds, int tb, const bf16* H, const bf16* Win_t, bf16* GT, float* DTt, float* At, const float* bg_f, const float* bg_b, ...
;     int tid_o_ = threadIdx.x; asm volatile("" : "+v"(tid_o_)); const int tid = tid_o_, lane = tid & 63, wave = __builtin_amdgcn_readfirstlane(tid >> 6);
;                 LAS float* PART = (LAS float*)lds; LAS float* LR = (LAS float*)(lds + 49152); LAS float* DTR = (LAS float*)(lds + 53248);
;                 {
;                     const int lr_ = lane & 15, lq_ = lane >> 4; pg8::f32x4 acc[2][3];
; #pragma unroll
;                     for (int rt = 0; rt < 2; ++rt)
; #pragma unroll
;                         for (int ct = 0; ct < 3; ++ct) acc[rt][ct] = (pg8::f32x4){0.f, 0.f, 0.f, 0.f};
;                     const bf16* hp = H + (size_t)(tb + lr_) * D + 128 * wave + 8 * lq_; const bf16* wp = Win_t + (size_t)(2816 + lr_) * D + 128 * wave + 8 * lq_;
;                     bf16x8 af[4][2], bfr[4][3];
; #pragma unroll
;                     for (int ks = 0; ks < 4; ++ks) {
; #pragma unroll
;                         for (int rt = 0; rt < 2; ++rt) af[ks][rt] = *(const bf16x8*)(hp + (size_t)(16 * rt) * D + 32 * ks);
; #pragma unroll
;                         for (int ct = 0; ct < 3; ++ct) bfr[ks][ct] = *(const bf16x8*)(wp + (size_t)(16 * ct) * D + 32 * ks); }
	v_cvt_pk_bf16_f32 v5, v45, 0
	v_lshlrev_b32_e32 v6, 16, v5
	v_sub_f32_e32 v6, v45, v6
	v_cvt_pk_bf16_f32 v6, v6, s0
	s_waitcnt vmcnt(3)
	v_cvt_pk_bf16_f32 v10, v37, 0
	v_cndmask_b32_e32 v9, 0, v6, vcc
	v_lshlrev_b32_e32 v6, 16, v10
	v_sub_f32_e32 v6, v37, v6
	v_cvt_pk_bf16_f32 v6, v6, s0
	v_cndmask_b32_e32 v17, 0, v6, vcc
	v_cvt_pk_bf16_f32 v6, v28, 0
	v_lshlrev_b32_e32 v7, 16, v6
	v_sub_f32_e32 v7, v28, v7
	v_cvt_pk_bf16_f32 v7, v7, s0
	v_cvt_pk_bf16_f32 v11, v29, 0
	v_cndmask_b32_e32 v18, 0, v7, vcc
	v_lshlrev_b32_e32 v7, 16, v11
	v_sub_f32_e32 v7, v29, v7
	v_cvt_pk_bf16_f32 v7, v7, s0
	v_cndmask_b32_e32 v20, 0, v7, vcc
	v_cvt_pk_bf16_f32 v7, v34, 0
	v_cvt_pk_bf16_f32 v22, v35, 0
	v_lshlrev_b32_e32 v21, 16, v7
	v_perm_b32 v4, v4, v1, s0
	v_lshlrev_b32_e32 v1, 16, v22
	v_sub_f32_e32 v21, v34, v21
	v_sub_f32_e32 v1, v35, v1
	v_cvt_pk_bf16_f32 v21, v21, s0
	v_cvt_pk_bf16_f32 v1, v1, s0
	v_cndmask_b32_e32 v21, 0, v21, vcc
	v_cndmask_b32_e32 v1, 0, v1, vcc
	v_perm_b32 v7, v22, v7, s0
	v_perm_b32 v6, v11, v6, s0
	v_perm_b32 v5, v10, v5, s0
	v_perm_b32 v11, v1, v21, s0
	v_cvt_pk_bf16_f32 v1, v2, 0
	v_perm_b32 v10, v20, v18, s0
	v_perm_b32 v9, v17, v9, s0
	v_perm_b32 v8, v12, v8, s0
	ds_write_b128 v19, v[4:7] offset:4096
	ds_write_b128 v19, v[8:11] offset:5120
	v_lshlrev_b32_e32 v4, 16, v1
	v_sub_f32_e32 v2, v2, v4
	s_waitcnt vmcnt(0)
	v_cvt_pk_bf16_f32 v4, v16, 0
	v_lshlrev_b32_e32 v5, 16, v4
	v_sub_f32_e32 v5, v16, v5
	v_cvt_pk_bf16_f32 v5, v5, s0
	v_cndmask_b32_e32 v8, 0, v5, vcc
	v_cvt_pk_bf16_f32 v5, v15, 0
	v_lshlrev_b32_e32 v6, 16, v5
	v_sub_f32_e32 v6, v15, v6
	v_cvt_pk_bf16_f32 v6, v6, s0
	v_cvt_pk_bf16_f32 v10, v13, 0
	v_cndmask_b32_e32 v9, 0, v6, vcc
	v_lshlrev_b32_e32 v6, 16, v10
	v_sub_f32_e32 v6, v13, v6
	v_cvt_pk_bf16_f32 v6, v6, s0
	v_cndmask_b32_e32 v12, 0, v6, vcc
	v_cvt_pk_bf16_f32 v6, v31, 0
	v_lshlrev_b32_e32 v7, 16, v6
	v_sub_f32_e32 v7, v31, v7
	v_cvt_pk_bf16_f32 v7, v7, s0
	v_cvt_pk_bf16_f32 v11, v30, 0
	v_cndmask_b32_e32 v13, 0, v7, vcc
	v_lshlrev_b32_e32 v7, 16, v11
	v_sub_f32_e32 v7, v30, v7
	v_cvt_pk_bf16_f32 v7, v7, s0
	v_cndmask_b32_e32 v15, 0, v7, vcc
	v_cvt_pk_bf16_f32 v7, v36, 0
	v_cvt_pk_bf16_f32 v17, v14, 0
	v_lshlrev_b32_e32 v16, 16, v7
	v_lshlrev_b32_e32 v18, 16, v17
	v_sub_f32_e32 v16, v36, v16
	v_sub_f32_e32 v14, v14, v18
	v_cvt_pk_bf16_f32 v2, v2, s0
	v_cvt_pk_bf16_f32 v16, v16, s0
	v_cvt_pk_bf16_f32 v14, v14, s0
	v_cndmask_b32_e32 v2, 0, v2, vcc
	v_cndmask_b32_e32 v16, 0, v16, vcc
	v_cndmask_b32_e32 v14, 0, v14, vcc
	v_perm_b32 v7, v17, v7, s0
	v_perm_b32 v6, v11, v6, s0
	v_perm_b32 v5, v10, v5, s0
	v_perm_b32 v4, v4, v1, s0
	v_mov_b32_e32 v1, v0
	v_perm_b32 v11, v14, v16, s0
	v_perm_b32 v10, v15, v13, s0
	v_perm_b32 v9, v12, v9, s0
	v_perm_b32 v8, v8, v2, s0
	ds_write_b128 v19, v[4:7] offset:6144
	ds_write_b128 v19, v[8:11] offset:7168
	s_nop 0
	v_readfirstlane_b32 s4, v1
	v_and_b32_e32 v34, 15, v1
	s_ashr_i32 s3, s4, 6
	v_or_b32_e32 v4, s19, v34
	v_ashrrev_i32_e32 v5, 31, v4
	s_lshl_b32 s0, s3, 7
	v_lshlrev_b64 v[4:5], 11, v[4:5]
	s_ashr_i32 s1, s0, 31
	v_lshl_add_u64 v[4:5], s[76:77], 0, v[4:5]
	s_lshl_b64 s[0:1], s[0:1], 1
	v_lshl_add_u64 v[4:5], v[4:5], 0, s[0:1]
	v_and_b32_e32 v2, 48, v1
	v_lshl_add_u64 v[64:65], v[4:5], 0, v[2:3]
	v_lshlrev_b32_e32 v4, 11, v34
	v_mov_b32_e32 v5, v3
	v_lshl_add_u64 v[4:5], s[8:9], 0, v[4:5]
	v_lshl_add_u64 v[4:5], v[4:5], 0, s[0:1]
	v_lshl_add_u64 v[44:45], v[4:5], 0, v[2:3]
	s_mov_b32 s0, 0x580000
	v_add_co_u32_e32 v6, vcc, s0, v44
	s_mov_b32 s0, 0x588000
	s_nop 0
	v_addc_co_u32_e32 v7, vcc, 0, v45, vcc
	v_add_co_u32_e32 v52, vcc, s0, v44
	s_nop 1
	v_addc_co_u32_e32 v53, vcc, 0, v45, vcc
	s_mov_b32 s0, 0x590000
	v_add_co_u32_e32 v66, vcc, s0, v44
	s_mov_b32 s0, 0x8000
	s_nop 0
	s_nop 1
	v_addc_co_u32_e32 v67, vcc, 0, v45, vcc
	v_add_co_u32_e32 v68, vcc, s0, v64
	s_nop 0
	s_nop 1
	v_addc_co_u32_e32 v69, vcc, 0, v65, vcc
	s_mov_b64 s[0:1], 0x580000
	v_lshl_add_u64 v[70:71], v[44:45], 0, s[0:1]
	global_load_dwordx4 v[148:151], v[64:65], off
	global_load_dwordx4 v[152:155], v[64:65], off offset:64
	global_load_dwordx4 v[156:159], v[64:65], off offset:128
	global_load_dwordx4 v[160:163], v[64:65], off offset:192
	global_load_dwordx4 v[164:167], v[68:69], off
	global_load_dwordx4 v[168:171], v[68:69], off offset:64
	global_load_dwordx4 v[172:175], v[68:69], off offset:128
	global_load_dwordx4 v[176:179], v[68:69], off offset:192
	global_load_dwordx4 v[180:183], v[70:71], off
	global_load_dwordx4 v[184:187], v[70:71], off offset:64
	global_load_dwordx4 v[188:191], v[70:71], off offset:128
	global_load_dwordx4 v[192:195], v[70:71], off offset:192
	global_load_dwordx4 v[196:199], v[52:53], off
	global_load_dwordx4 v[200:203], v[52:53], off offset:64
	global_load_dwordx4 v[204:207], v[52:53], off offset:128
	global_load_dwordx4 v[208:211], v[52:53], off offset:192
	global_load_dwordx4 v[212:215], v[66:67], off
	global_load_dwordx4 v[216:219], v[66:67], off offset:64
	global_load_dwordx4 v[220:223], v[66:67], off offset:128
	global_load_dwordx4 v[224:227], v[66:67], off offset:192
	s_cmpk_lt_u32 s4, 0x100
	s_cselect_b32 s1, s65, s37
	s_cselect_b32 s0, s64, s36
	s_and_b32 s5, s4, 0xc0
	v_bfe_u32 v35, v1, 4, 2
	v_or_b32_e32 v42, s5, v34
	v_lshlrev_b32_e32 v43, 2, v35
	v_and_b32_e32 v44, 63, v1
	s_waitcnt vmcnt(0)
; #define LAS __attribute__((address_space(3)))
; #define MFMA16(a, b, c) __builtin_amdgcn_mfma_f32_16x16x32_bf16((a), (b), (c), 0, 0, 0)
; __device__ __forceinline__ void gate_half_item(LAS unsigned char* lds, int tb, const bf16* H, const bf16* Win_t, bf16* GT, float* DTt, float* At, const float* bg_f, const float* bg_b, ...
;     ...
; #pragma unroll
;                     for (int ks = 0; ks < 4; ++ks)
; #pragma unroll
;                         for (int rt = 0; rt < 2; ++rt)
; #pragma unroll
;                             for (int ct = 0; ct < 3; ++ct) acc[rt][ct] = MFMA16(af[ks][rt], bfr[ks][ct], acc[rt][ct]);
; #pragma unroll
;                     for (int rt = 0; rt < 2; ++rt)
; #pragma unroll
;                         for (int ct = 0; ct < 3; ++ct)
; #pragma unroll
;                             for (int r = 0; r < 4; ++r) PART[(wave * 32 + 16 * rt + 4 * lq_ + r) * 48 + 16 * ct + lr_] = acc[rt][ct][r];
;                 }
;                 const int d = wave >> 2, lr_g = lane & 15, lq_g = lane >> 4; bf16* Gd = GT + (size_t)d * MALL * 256;
;                 bf16x8 B1[4], B2[4]; float bgc[4];
; #pragma unroll
;                 for (int c4 = 0; c4 < 4; ++c4) { bgc[c4] = (d ? bg_b : bg_f)[16 * (4 * (wave & 3) + c4) + lr_g];
;                     B1[c4] = *(const LAS bf16x8*)(lds + 65536 + ((wave * 8 + c4 * 2) * 64 + lane) * 16); B2[c4] = *(const LAS bf16x8*)(lds + 65536 + ((wave * 8 + c4 * 2 + 1) * 64 + lane) * 16); }
;                 __syncthreads();
; #pragma unroll
;                 for (int i = 0; i < 3; ++i) { const int idx = tid + NT * i, tok = idx / 48, col2 = idx % 48; float v = 0.f;
; #pragma unroll
;                     for (int w8 = 0; w8 < 8; ++w8) v += PART[(w8 * 32 + tok) * 48 + col2];
;                     if (col2 < 32) LR[tok * 32 + col2] = v; else DTR[tok * 16 + col2 - 32] = v; }
	v_mfma_f32_16x16x32_bf16 v[18:21], v[148:151], v[180:183], 0
	v_mfma_f32_16x16x32_bf16 v[26:29], v[148:151], v[196:199], 0
	v_mfma_f32_16x16x32_bf16 v[2:5], v[148:151], v[212:215], 0
	v_mfma_f32_16x16x32_bf16 v[6:9], v[164:167], v[180:183], 0
	v_mfma_f32_16x16x32_bf16 v[10:13], v[164:167], v[196:199], 0
	v_mfma_f32_16x16x32_bf16 v[14:17], v[164:167], v[212:215], 0
	v_mfma_f32_16x16x32_bf16 v[18:21], v[152:155], v[184:187], v[18:21]
	v_mfma_f32_16x16x32_bf16 v[26:29], v[152:155], v[200:203], v[26:29]
	v_mfma_f32_16x16x32_bf16 v[2:5], v[152:155], v[216:219], v[2:5]
	v_mfma_f32_16x16x32_bf16 v[6:9], v[168:171], v[184:187], v[6:9]
	v_mfma_f32_16x16x32_bf16 v[10:13], v[168:171], v[200:203], v[10:13]
	v_mfma_f32_16x16x32_bf16 v[14:17], v[168:171], v[216:219], v[14:17]
	v_mfma_f32_16x16x32_bf16 v[18:21], v[156:159], v[188:191], v[18:21]
	v_mfma_f32_16x16x32_bf16 v[26:29], v[156:159], v[204:207], v[26:29]
	v_mfma_f32_16x16x32_bf16 v[2:5], v[156:159], v[220:223], v[2:5]
	v_mfma_f32_16x16x32_bf16 v[6:9], v[172:175], v[188:191], v[6:9]
	v_mfma_f32_16x16x32_bf16 v[10:13], v[172:175], v[204:207], v[10:13]
	v_mfma_f32_16x16x32_bf16 v[14:17], v[172:175], v[220:223], v[14:17]
	v_mfma_f32_16x16x32_bf16 v[18:21], v[160:163], v[192:195], v[18:21]
	v_mfma_f32_16x16x32_bf16 v[26:29], v[160:163], v[208:211], v[26:29]
	v_mfma_f32_16x16x32_bf16 v[2:5], v[160:163], v[224:227], v[2:5]
	v_mfma_f32_16x16x32_bf16 v[6:9], v[176:179], v[192:195], v[6:9]
	v_mfma_f32_16x16x32_bf16 v[10:13], v[176:179], v[208:211], v[10:13]
	v_mfma_f32_16x16x32_bf16 v[14:17], v[176:179], v[224:227], v[14:17]
	s_nop 7
	s_nop 1
	v_lshlrev_b32_e32 v22, 2, v42
	global_load_dword v49, v22, s[0:1]
	global_load_dword v48, v22, s[0:1] offset:64
	global_load_dword v47, v22, s[0:1] offset:128
	global_load_dword v46, v22, s[0:1] offset:192
	s_movk_i32 s0, 0xc0
	v_lshl_or_b32 v22, s3, 5, v43
	v_lshlrev_b32_e32 v23, 2, v34
	v_mul_lo_u32 v22, v22, s0
	v_add3_u32 v22, 0, v23, v22
	s_lshl_b32 s1, s3, 13
	s_add_i32 s1, s33, s1
	ds_write2_b32 v22, v18, v26 offset1:16
	ds_write2_b32 v22, v20, v28 offset0:96 offset1:112
	s_nop 5
	ds_write2_b32 v22, v2, v19 offset0:32 offset1:48
	ds_write2_b32 v22, v27, v3 offset0:64 offset1:80
	ds_write2_b32 v22, v4, v21 offset0:128 offset1:144
	ds_write2_b32 v22, v29, v5 offset0:160 offset1:176
	v_add_u32_e32 v2, 0xc00, v22
	ds_write2_b32 v2, v6, v10 offset1:16
	ds_write2_b32 v2, v8, v12 offset0:96 offset1:112
	s_nop 5
	ds_write2_b32 v2, v14, v7 offset0:32 offset1:48
	ds_write2_b32 v2, v11, v15 offset0:64 offset1:80
	ds_write2_b32 v2, v16, v9 offset0:128 offset1:144
	ds_write2_b32 v2, v13, v17 offset0:160 offset1:176
	v_lshl_add_u32 v2, v44, 4, s1
	s_mov_b32 s1, 0x2aaaaaab
	v_mul_hi_i32 v36, v1, s1
	v_lshrrev_b32_e32 v37, 31, v36
	v_ashrrev_i32_e32 v36, 3, v36
	v_add_u32_e32 v36, v36, v37
	v_mul_lo_u32 v37, v36, 48
	v_sub_u32_e32 v45, v1, v37
	v_lshlrev_b32_e32 v37, 2, v45
	v_mul_lo_u32 v38, v36, s0
	v_add3_u32 v52, 0, v37, v38
	ds_read_b128 v[30:33], v2
	ds_read_b128 v[26:29], v2 offset:1024
	ds_read_b128 v[22:25], v2 offset:2048
	ds_read_b128 v[18:21], v2 offset:3072
	ds_read_b128 v[14:17], v2 offset:4096
	ds_read_b128 v[10:13], v2 offset:5120
	ds_read_b128 v[6:9], v2 offset:6144
	ds_read_b128 v[2:5], v2 offset:7168
	s_waitcnt lgkmcnt(0)
	s_barrier
	ds_read2st64_b32 v[38:39], v52 offset1:24
	ds_read2st64_b32 v[40:41], v52 offset0:48 offset1:72
	ds_read2st64_b32 v[50:51], v52 offset0:96 offset1:120
	v_cmp_lt_i32_e32 vcc, 31, v45
	s_waitcnt lgkmcnt(2)
	v_add_f32_e32 v38, 0, v38
	v_add_f32_e32 v53, v38, v39
	ds_read2st64_b32 v[38:39], v52 offset0:144 offset1:168
	s_waitcnt lgkmcnt(2)
	v_add_f32_e32 v40, v53, v40
	v_add_f32_e32 v40, v40, v41
	s_waitcnt lgkmcnt(1)
	v_add_f32_e32 v40, v40, v50
	v_add_f32_e32 v40, v40, v51
	s_waitcnt lgkmcnt(0)
	v_add_f32_e32 v38, v40, v38
	v_add_f32_e32 v38, v38, v39
	s_and_saveexec_b64 s[0:1], vcc
	s_xor_b64 s[0:1], exec, s[0:1]
	v_lshlrev_b32_e32 v36, 6, v36
	v_add3_u32 v36, 0, v36, v37
	ds_write_b32 v36, v38 offset:53120
	s_andn2_saveexec_b64 s[0:1], s[0:1]
	v_lshlrev_b32_e32 v36, 7, v36
	v_add3_u32 v36, 0, v36, v37
	ds_write_b32 v36, v38 offset:49152
	s_or_b64 exec, exec, s[0:1]
	v_add_u32_e32 v37, 0x200, v1
	s_mov_b32 s0, 0x2aaaaaab
	v_mul_hi_i32 v36, v37, s0
	v_lshrrev_b32_e32 v38, 31, v36
	v_ashrrev_i32_e32 v36, 3, v36
	v_add_u32_e32 v36, v36, v38
	v_mul_lo_u32 v38, v36, 48
	v_sub_u32_e32 v45, v37, v38
	s_movk_i32 s0, 0xc0
	v_lshlrev_b32_e32 v37, 2, v45
	v_mul_lo_u32 v38, v36, s0
	v_add3_u32 v52, 0, v37, v38
	ds_read2st64_b32 v[38:39], v52 offset1:24
	ds_read2st64_b32 v[40:41], v52 offset0:48 offset1:72
	ds_read2st64_b32 v[50:51], v52 offset0:96 offset1:120
	v_cmp_lt_i32_e32 vcc, 31, v45
	s_waitcnt lgkmcnt(2)
	v_add_f32_e32 v38, 0, v38
	v_add_f32_e32 v53, v38, v39
	ds_read2st64_b32 v[38:39], v52 offset0:144 offset1:168
	s_waitcnt lgkmcnt(2)
	v_add_f32_e32 v40, v53, v40
	v_add_f32_e32 v40, v40, v41
	s_waitcnt lgkmcnt(1)
	v_add_f32_e32 v40, v40, v50
	v_add_f32_e32 v40, v40, v51
	s_waitcnt lgkmcnt(0)
	v_add_f32_e32 v38, v40, v38
	v_add_f32_e32 v38, v38, v39
	s_and_saveexec_b64 s[0:1], vcc
	s_xor_b64 s[0:1], exec, s[0:1]
	v_lshlrev_b32_e32 v36, 6, v36
	v_add3_u32 v36, 0, v36, v37
	ds_write_b32 v36, v38 offset:53120
	s_andn2_saveexec_b64 s[0:1], s[0:1]
	v_lshlrev_b32_e32 v36, 7, v36
	v_add3_u32 v36, 0, v36, v37
	ds_write_b32 v36, v38 offset:49152
	s_or_b64 exec, exec, s[0:1]
	v_add_u32_e32 v37, 0x400, v1
	s_mov_b32 s0, 0x2aaaaaab
	v_mul_hi_i32 v36, v37, s0
	v_lshrrev_b32_e32 v38, 31, v36
	v_ashrrev_i32_e32 v36, 3, v36
	v_add_u32_e32 v36, v36, v38
	v_mul_lo_u32 v38, v36, 48
	v_sub_u32_e32 v45, v37, v38
	s_movk_i32 s0, 0xc0
	v_lshlrev_b32_e32 v37, 2, v45
	v_mul_lo_u32 v38, v36, s0
	v_add3_u32 v52, 0, v37, v38
	ds_read2st64_b32 v[38:39], v52 offset1:24
	ds_read2st64_b32 v[40:41], v52 offset0:48 offset1:72
	ds_read2st64_b32 v[50:51], v52 offset0:96 offset1:120
	v_cmp_lt_i32_e32 vcc, 31, v45
	s_waitcnt lgkmcnt(2)
	v_add_f32_e32 v38, 0, v38
	v_add_f32_e32 v53, v38, v39
	ds_read2st64_b32 v[38:39], v52 offset0:144 offset1:168
	s_waitcnt lgkmcnt(2)
	v_add_f32_e32 v40, v53, v40
	v_add_f32_e32 v40, v40, v41
	s_waitcnt lgkmcnt(1)
	v_add_f32_e32 v40, v40, v50
	v_add_f32_e32 v40, v40, v51
	s_waitcnt lgkmcnt(0)
	v_add_f32_e32 v38, v40, v38
	v_add_f32_e32 v38, v38, v39
	s_and_saveexec_b64 s[0:1], vcc
	s_xor_b64 s[0:1], exec, s[0:1]
	v_lshlrev_b32_e32 v36, 6, v36
	v_add3_u32 v36, 0, v36, v37
	ds_write_b32 v36, v38 offset:53120
	s_or_saveexec_b64 s[0:1], s[0:1]
	v_lshlrev_b32_e32 v35, 3, v35
	s_xor_b64 exec, exec, s[0:1]
	v_lshlrev_b32_e32 v36, 7, v36
	v_add3_u32 v36, 0, v36, v37
	ds_write_b32 v36, v38 offset:49152
	s_or_b64 exec, exec, s[0:1]
	s_ashr_i32 s3, s4, 8
	s_lshl_b32 s0, s3, 6
	s_add_i32 s0, s0, 0
	v_and_b32_e32 v35, 8, v35
	v_lshl_add_u32 v35, v35, 2, s0
	v_lshlrev_b32_e32 v34, 7, v34
	v_add_u32_e32 v50, v35, v34
	s_waitcnt lgkmcnt(0)
	s_barrier
; #define LAS __attribute__((address_space(3)))
; __device__ __forceinline__ unsigned f2bf(float f) { return pk2(f, 0.f) & 0xffffu; }
; #define MFMA16(a, b, c) __builtin_amdgcn_mfma_f32_16x16x32_bf16((a), (b), (c), 0, 0, 0)
; __device__ __forceinline__ void gate_half_item(LAS unsigned char* lds, int tb, const bf16* H, const bf16* Win_t, bf16* GT, float* DTt, float* At, const float* bg_f, const float* bg_b, ...
;     ...
;                 for (int rt = 0; rt < 2; ++rt) { bf16x8 A1, A2;
;                     { const LAS f32x4* lp = (const LAS f32x4*)(LR + (16 * rt + lr_g) * 32 + 16 * d + ((8 * lq_g) & 15)); const f32x4 l0 = lp[0], l1 = lp[1]; const float lv[8] = {l0.x, l0.y, l0.z, l0.w, l1.x, l1.y, l1.z, l1.w};
; #pragma unroll
;                       for (int e = 0; e < 8; ++e) { const unsigned hi = f2bf(lv[e]); const float rem = lv[e] - __builtin_bit_cast(float, hi << 16);
;                           A1[e] = (lq_g < 2) ? (short)hi : (short)f2bf(rem); A2[e] = (lq_g < 2) ? (short)hi : (short)0; } }
; #pragma unroll
;                     for (int c4 = 0; c4 < 4; ++c4) { pg8::f32x4 acc = {0.f, 0.f, 0.f, 0.f}; acc = MFMA16(A1, B1[c4], acc); acc = MFMA16(A2, B2[c4], acc);
;                         const int colc = 16 * (4 * (wave & 3) + c4) + lr_g;
; #pragma unroll
;                         for (int r = 0; r < 4; ++r) { const float dot = acc[r] + bgc[c4];
;                             Gd[(size_t)(tb + 16 * rt + 4 * lq_g + r) * 256 + colc] = (bf16)f2bf((fminf(dot, 0.f) - 0.69314718056f * __builtin_amdgcn_logf(1.0f + __builtin_amdgcn_exp2f(-1.44269504089f * fabsf(dot)))) * (1.0f / 16.0f)); } } }
	ds_read_b128 v[38:41], v50 offset:49152
	ds_read_b128 v[34:37], v50 offset:49168
	v_cmp_gt_u32_e32 vcc, 32, v44
	v_cmp_lt_u32_e64 s[4:5], 31, v44
	s_waitcnt lgkmcnt(1)
	v_cvt_pk_bf16_f32 v45, v38, 0
	v_and_b32_e32 v44, 0xffff, v45
	s_and_saveexec_b64 s[0:1], s[4:5]
	v_lshlrev_b32_e32 v44, 16, v44
	v_sub_f32_e32 v38, v38, v44
	v_cvt_pk_bf16_f32 v44, v38, 0
	s_or_b64 exec, exec, s[0:1]
	v_cvt_pk_bf16_f32 v51, v39, 0
	v_and_b32_e32 v38, 0xffff, v51
	s_and_saveexec_b64 s[0:1], s[4:5]
	v_lshlrev_b32_e32 v38, 16, v38
	v_sub_f32_e32 v38, v39, v38
	v_cvt_pk_bf16_f32 v38, v38, 0
	s_or_b64 exec, exec, s[0:1]
	v_cvt_pk_bf16_f32 v52, v40, 0
	v_and_b32_e32 v39, 0xffff, v52
	s_and_saveexec_b64 s[0:1], s[4:5]
	v_lshlrev_b32_e32 v39, 16, v39
	v_sub_f32_e32 v39, v40, v39
	v_cvt_pk_bf16_f32 v39, v39, 0
	s_or_b64 exec, exec, s[0:1]
	v_cvt_pk_bf16_f32 v53, v41, 0
	v_and_b32_e32 v40, 0xffff, v53
	s_and_saveexec_b64 s[0:1], s[4:5]
	v_lshlrev_b32_e32 v40, 16, v40
	v_sub_f32_e32 v40, v41, v40
	v_cvt_pk_bf16_f32 v40, v40, 0
	s_or_b64 exec, exec, s[0:1]
	s_waitcnt lgkmcnt(0)
	v_cvt_pk_bf16_f32 v54, v34, 0
	v_and_b32_e32 v41, 0xffff, v54
	s_and_saveexec_b64 s[0:1], s[4:5]
	v_lshlrev_b32_e32 v41, 16, v41
	v_sub_f32_e32 v34, v34, v41
	v_cvt_pk_bf16_f32 v41, v34, 0
	s_or_b64 exec, exec, s[0:1]
	v_cvt_pk_bf16_f32 v55, v35, 0
	v_and_b32_e32 v34, 0xffff, v55
	s_and_saveexec_b64 s[0:1], s[4:5]
	v_lshlrev_b32_e32 v34, 16, v34
	v_sub_f32_e32 v34, v35, v34
	v_cvt_pk_bf16_f32 v34, v34, 0
	s_or_b64 exec, exec, s[0:1]
	v_cvt_pk_bf16_f32 v56, v36, 0
	v_and_b32_e32 v35, 0xffff, v56
	s_and_saveexec_b64 s[0:1], s[4:5]
	v_lshlrev_b32_e32 v35, 16, v35
	v_sub_f32_e32 v35, v36, v35
	v_cvt_pk_bf16_f32 v35, v35, 0
	s_or_b64 exec, exec, s[0:1]
	v_cvt_pk_bf16_f32 v36, v37, 0
	v_and_b32_e32 v57, 0xffff, v36
	s_and_saveexec_b64 s[0:1], s[4:5]
	v_lshlrev_b32_e32 v57, 16, v57
	v_sub_f32_e32 v37, v37, v57
	v_cvt_pk_bf16_f32 v57, v37, 0
	s_or_b64 exec, exec, s[0:1]
	s_mov_b32 s0, 0x5040100
	v_cndmask_b32_e32 v58, 0, v36, vcc
	v_perm_b32 v37, v57, v35, s0
	v_perm_b32 v36, v34, v41, s0
	v_perm_b32 v35, v40, v39, s0
	v_perm_b32 v34, v38, v44, s0
	v_cndmask_b32_e32 v45, 0, v45, vcc
	v_cndmask_b32_e32 v51, 0, v51, vcc
	v_cndmask_b32_e32 v52, 0, v52, vcc
	v_cndmask_b32_e32 v53, 0, v53, vcc
	v_cndmask_b32_e32 v54, 0, v54, vcc
	v_cndmask_b32_e32 v55, 0, v55, vcc
	v_cndmask_b32_e32 v56, 0, v56, vcc
	v_perm_b32 v41, v58, v56, s0
	v_perm_b32 v40, v55, v54, s0
	v_perm_b32 v39, v53, v52, s0
	v_perm_b32 v38, v51, v45, s0
	v_mfma_f32_16x16x32_bf16 v[52:55], v[34:37], v[30:33], 0
	s_add_u32 s0, s78, 0x9200000
	s_mul_hi_i32 s1, s3, 0x880000
	s_mul_i32 s3, s3, 0x880000
	v_mfma_f32_16x16x32_bf16 v[52:55], v[38:41], v[26:29], v[52:55]
	s_addc_u32 s7, s79, 0
	v_writelane_b32 v240, s0, 32
	s_add_u32 s6, s0, s3
	s_mov_b32 s0, 0xbfb8aa3b
	v_writelane_b32 v240, s7, 33
	s_waitcnt vmcnt(3)
	s_nop 1
	v_add_f32_e32 v45, v49, v52
	v_mul_f32_e64 v44, |v45|, s0
	v_exp_f32_e32 v51, v44
	v_or_b32_e32 v44, s19, v43
	v_min_f32_e32 v45, 0, v45
	s_addc_u32 s7, s7, s1
	v_add_f32_e32 v43, 1.0, v51
	v_log_f32_e32 v51, v43
	v_lshlrev_b32_e32 v42, 1, v42
	v_mov_b32_e32 v43, 0
	v_lshl_add_u64 v[42:43], s[6:7], 0, v[42:43]
	v_fmac_f32_e32 v45, 0xbf317218, v51
	v_add_f32_e32 v51, v49, v53
	v_mul_f32_e64 v52, |v51|, s0
	v_exp_f32_e32 v56, v52
	v_mul_f32_e32 v45, 0x3d800000, v45
	v_cvt_pk_bf16_f32 v58, v45, s0
	v_ashrrev_i32_e32 v45, 31, v44
	v_lshlrev_b64 v[52:53], 9, v[44:45]
	v_add_f32_e32 v45, 1.0, v56
	v_log_f32_e32 v45, v45
	v_min_f32_e32 v51, 0, v51
	v_lshl_add_u64 v[56:57], v[42:43], 0, v[52:53]
	global_store_short v[56:57], v58, off
	v_fmac_f32_e32 v51, 0xbf317218, v45
	v_mul_f32_e32 v45, 0x3d800000, v51
	v_add_f32_e32 v51, v49, v54
	v_mul_f32_e64 v52, |v51|, s0
	v_exp_f32_e32 v54, v52
	v_or_b32_e32 v52, 1, v44
	v_ashrrev_i32_e32 v53, 31, v52
	v_lshlrev_b64 v[52:53], 9, v[52:53]
	v_add_f32_e32 v54, 1.0, v54
	v_log_f32_e32 v54, v54
	v_cvt_pk_bf16_f32 v45, v45, s0
	v_lshl_add_u64 v[58:59], v[42:43], 0, v[52:53]
	global_store_short v[58:59], v45, off
	v_min_f32_e32 v45, 0, v51
	v_add_f32_e32 v51, v49, v55
	v_mul_f32_e64 v52, |v51|, s0
	v_fmac_f32_e32 v45, 0xbf317218, v54
	v_exp_f32_e32 v54, v52
	v_or_b32_e32 v52, 2, v44
	v_ashrrev_i32_e32 v53, 31, v52
	v_mul_f32_e32 v45, 0x3d800000, v45
	v_add_f32_e32 v54, 1.0, v54
	v_log_f32_e32 v54, v54
	v_lshlrev_b64 v[52:53], 9, v[52:53]
	v_cvt_pk_bf16_f32 v45, v45, s0
	v_lshl_add_u64 v[60:61], v[42:43], 0, v[52:53]
	global_store_short v[60:61], v45, off
	v_min_f32_e32 v45, 0, v51
	v_fmac_f32_e32 v45, 0xbf317218, v54
	v_mfma_f32_16x16x32_bf16 v[52:55], v[34:37], v[22:25], 0
	v_or_b32_e32 v62, 3, v44
	v_ashrrev_i32_e32 v63, 31, v62
	v_mul_f32_e32 v45, 0x3d800000, v45
	v_mfma_f32_16x16x32_bf16 v[52:55], v[38:41], v[18:21], v[52:55]
	v_lshlrev_b64 v[62:63], 9, v[62:63]
	v_cvt_pk_bf16_f32 v45, v45, s0
	v_lshl_add_u64 v[62:63], v[42:43], 0, v[62:63]
	global_store_short v[62:63], v45, off
	s_waitcnt vmcnt(6)
	s_nop 2
	v_add_f32_e32 v51, v48, v52
	v_mul_f32_e64 v52, |v51|, s0
	v_exp_f32_e32 v52, v52
	v_min_f32_e32 v51, 0, v51
	v_add_f32_e32 v64, v48, v55
	v_add_f32_e32 v45, 1.0, v52
	v_add_f32_e32 v52, v48, v53
	v_log_f32_e32 v45, v45
	v_mul_f32_e64 v53, |v52|, s0
	v_exp_f32_e32 v53, v53
	v_fmac_f32_e32 v51, 0xbf317218, v45
	v_mul_f32_e32 v45, 0x3d800000, v51
	v_add_f32_e32 v51, 1.0, v53
	v_log_f32_e32 v51, v51
	v_cvt_pk_bf16_f32 v45, v45, s0
	global_store_short v[56:57], v45, off offset:32
	v_min_f32_e32 v45, 0, v52
	v_fmac_f32_e32 v45, 0xbf317218, v51
	v_add_f32_e32 v51, v48, v54
	v_mul_f32_e64 v52, |v51|, s0
	v_exp_f32_e32 v52, v52
	v_mul_f32_e32 v45, 0x3d800000, v45
	v_cvt_pk_bf16_f32 v45, v45, s0
	global_store_short v[58:59], v45, off offset:32
	v_min_f32_e32 v45, 0, v51
	v_add_f32_e32 v51, 1.0, v52
	v_mul_f32_e64 v52, |v64|, s0
	v_log_f32_e32 v51, v51
	v_exp_f32_e32 v52, v52
	v_fmac_f32_e32 v45, 0xbf317218, v51
	v_add_f32_e32 v51, 1.0, v52
	v_mfma_f32_16x16x32_bf16 v[52:55], v[34:37], v[14:17], 0
	v_log_f32_e32 v51, v51
	v_mul_f32_e32 v45, 0x3d800000, v45
	v_cvt_pk_bf16_f32 v45, v45, s0
	v_mfma_f32_16x16x32_bf16 v[52:55], v[38:41], v[10:13], v[52:55]
	global_store_short v[60:61], v45, off offset:32
	v_min_f32_e32 v45, 0, v64
	v_fmac_f32_e32 v45, 0xbf317218, v51
	v_mul_f32_e32 v45, 0x3d800000, v45
	v_cvt_pk_bf16_f32 v45, v45, s0
	s_waitcnt vmcnt(8)
; #define LAS __attribute__((address_space(3)))
; __device__ __forceinline__ unsigned f2bf(float f) { return pk2(f, 0.f) & 0xffffu; }
; #define MFMA16(a, b, c) __builtin_amdgcn_mfma_f32_16x16x32_bf16((a), (b), (c), 0, 0, 0)
; __device__ __forceinline__ void gate_half_item(LAS unsigned char* lds, int tb, const bf16* H, const bf16* Win_t, bf16* GT, float* DTt, float* At, const float* bg_f, const float* bg_b, ...
;     ...
;                 for (int rt = 0; rt < 2; ++rt) { bf16x8 A1, A2;
;                     { const LAS f32x4* lp = (const LAS f32x4*)(LR + (16 * rt + lr_g) * 32 + 16 * d + ((8 * lq_g) & 15)); const f32x4 l0 = lp[0], l1 = lp[1]; const float lv[8] = {l0.x, l0.y, l0.z, l0.w, l1.x, l1.y, l1.z, l1.w};
; #pragma unroll
;                       for (int e = 0; e < 8; ++e) { const unsigned hi = f2bf(lv[e]); const float rem = lv[e] - __builtin_bit_cast(float, hi << 16);
;                           A1[e] = (lq_g < 2) ? (short)hi : (short)f2bf(rem); A2[e] = (lq_g < 2) ? (short)hi : (short)0; } }
; #pragma unroll
;                     for (int c4 = 0; c4 < 4; ++c4) { pg8::f32x4 acc = {0.f, 0.f, 0.f, 0.f}; acc = MFMA16(A1, B1[c4], acc); acc = MFMA16(A2, B2[c4], acc);
;                         const int colc = 16 * (4 * (wave & 3) + c4) + lr_g;
; #pragma unroll
;                         for (int r = 0; r < 4; ++r) { const float dot = acc[r] + bgc[c4];
;                             Gd[(size_t)(tb + 16 * rt + 4 * lq_g + r) * 256 + colc] = (bf16)f2bf((fminf(dot, 0.f) - 0.69314718056f * __builtin_amdgcn_logf(1.0f + __builtin_amdgcn_exp2f(-1.44269504089f * fabsf(dot)))) * (1.0f / 16.0f)); } } }
	s_nop 1
	v_add_f32_e32 v51, v47, v52
	v_mul_f32_e64 v52, |v51|, s0
	v_exp_f32_e32 v52, v52
	global_store_short v[62:63], v45, off offset:32
	v_min_f32_e32 v51, 0, v51
	v_mfma_f32_16x16x32_bf16 v[34:37], v[34:37], v[6:9], 0
	v_add_f32_e32 v45, 1.0, v52
	v_add_f32_e32 v52, v47, v53
	v_log_f32_e32 v45, v45
	v_mul_f32_e64 v53, |v52|, s0
	v_exp_f32_e32 v53, v53
	v_mfma_f32_16x16x32_bf16 v[34:37], v[38:41], v[2:5], v[34:37]
	v_fmac_f32_e32 v51, 0xbf317218, v45
	v_mul_f32_e32 v45, 0x3d800000, v51
	v_add_f32_e32 v51, 1.0, v53
	v_log_f32_e32 v51, v51
	v_cvt_pk_bf16_f32 v45, v45, s0
	global_store_short v[56:57], v45, off offset:64
	v_min_f32_e32 v45, 0, v52
	v_fmac_f32_e32 v45, 0xbf317218, v51
	v_add_f32_e32 v51, v47, v54
	v_mul_f32_e64 v52, |v51|, s0
	v_exp_f32_e32 v52, v52
	v_mul_f32_e32 v45, 0x3d800000, v45
	v_cvt_pk_bf16_f32 v45, v45, s0
	global_store_short v[58:59], v45, off offset:64
	v_min_f32_e32 v45, 0, v51
	v_add_f32_e32 v51, 1.0, v52
	v_add_f32_e32 v52, v47, v55
	v_mul_f32_e64 v53, |v52|, s0
	v_log_f32_e32 v51, v51
	v_exp_f32_e32 v53, v53
	s_waitcnt vmcnt(10)
	v_add_f32_e32 v34, v46, v34
	v_mul_f32_e64 v38, |v34|, s0
	v_fmac_f32_e32 v45, 0xbf317218, v51
	v_add_f32_e32 v51, 1.0, v53
	v_log_f32_e32 v51, v51
	v_mul_f32_e32 v45, 0x3d800000, v45
	v_cvt_pk_bf16_f32 v45, v45, s0
	v_exp_f32_e32 v38, v38
	global_store_short v[60:61], v45, off offset:64
	v_min_f32_e32 v45, 0, v52
	v_fmac_f32_e32 v45, 0xbf317218, v51
	v_mul_f32_e32 v39, 0x3d800000, v45
	v_cvt_pk_bf16_f32 v39, v39, s0
	v_add_f32_e32 v38, 1.0, v38
	v_add_f32_e32 v35, v46, v35
	global_store_short v[62:63], v39, off offset:64
	v_log_f32_e32 v38, v38
	v_mul_f32_e64 v39, |v35|, s0
	v_exp_f32_e32 v39, v39
	v_min_f32_e32 v34, 0, v34
	v_fmac_f32_e32 v34, 0xbf317218, v38
	v_mul_f32_e32 v34, 0x3d800000, v34
	v_add_f32_e32 v38, 1.0, v39
	v_log_f32_e32 v38, v38
	v_cvt_pk_bf16_f32 v34, v34, s0
	global_store_short v[56:57], v34, off offset:96
	v_min_f32_e32 v34, 0, v35
	v_add_f32_e32 v35, v46, v36
	v_mul_f32_e64 v36, |v35|, s0
	v_exp_f32_e32 v36, v36
	v_fmac_f32_e32 v34, 0xbf317218, v38
	v_mul_f32_e32 v34, 0x3d800000, v34
	v_cvt_pk_bf16_f32 v34, v34, s0
	global_store_short v[58:59], v34, off offset:96
	v_add_f32_e32 v34, 1.0, v36
	v_add_f32_e32 v36, v46, v37
	v_log_f32_e32 v34, v34
	v_mul_f32_e64 v37, |v36|, s0
	v_exp_f32_e32 v37, v37
	v_min_f32_e32 v35, 0, v35
	v_fmac_f32_e32 v35, 0xbf317218, v34
	v_mul_f32_e32 v34, 0x3d800000, v35
	v_add_f32_e32 v35, 1.0, v37
	v_log_f32_e32 v35, v35
	v_cvt_pk_bf16_f32 v34, v34, s0
	global_store_short v[60:61], v34, off offset:96
	v_min_f32_e32 v34, 0, v36
	ds_read_b128 v[38:41], v50 offset:51200
	v_fmac_f32_e32 v34, 0xbf317218, v35
	v_mul_f32_e32 v45, 0x3d800000, v34
	ds_read_b128 v[34:37], v50 offset:51216
	v_cvt_pk_bf16_f32 v45, v45, s0
	global_store_short v[62:63], v45, off offset:96
	s_waitcnt lgkmcnt(1)
	v_cvt_pk_bf16_f32 v45, v38, 0
	v_and_b32_e32 v50, 0xffff, v45
	s_and_saveexec_b64 s[0:1], s[4:5]
	v_lshlrev_b32_e32 v50, 16, v50
	v_sub_f32_e32 v38, v38, v50
	v_cvt_pk_bf16_f32 v50, v38, 0
	s_or_b64 exec, exec, s[0:1]
	v_cvt_pk_bf16_f32 v51, v39, 0
	v_and_b32_e32 v38, 0xffff, v51
	s_and_saveexec_b64 s[0:1], s[4:5]
	v_lshlrev_b32_e32 v38, 16, v38
	v_sub_f32_e32 v38, v39, v38
	v_cvt_pk_bf16_f32 v38, v38, 0
	s_or_b64 exec, exec, s[0:1]
	v_cvt_pk_bf16_f32 v52, v40, 0
	v_and_b32_e32 v39, 0xffff, v52
	s_and_saveexec_b64 s[0:1], s[4:5]
	v_lshlrev_b32_e32 v39, 16, v39
	v_sub_f32_e32 v39, v40, v39
	v_cvt_pk_bf16_f32 v39, v39, 0
	s_or_b64 exec, exec, s[0:1]
	v_cvt_pk_bf16_f32 v53, v41, 0
	v_and_b32_e32 v40, 0xffff, v53
	s_and_saveexec_b64 s[0:1], s[4:5]
	v_lshlrev_b32_e32 v40, 16, v40
	v_sub_f32_e32 v40, v41, v40
	v_cvt_pk_bf16_f32 v40, v40, 0
	s_or_b64 exec, exec, s[0:1]
	s_waitcnt lgkmcnt(0)
	v_cvt_pk_bf16_f32 v55, v34, 0
	v_and_b32_e32 v41, 0xffff, v55
	s_and_saveexec_b64 s[0:1], s[4:5]
	v_lshlrev_b32_e32 v41, 16, v41
	v_sub_f32_e32 v34, v34, v41
	v_cvt_pk_bf16_f32 v41, v34, 0
	s_or_b64 exec, exec, s[0:1]
	v_cvt_pk_bf16_f32 v56, v35, 0
	v_and_b32_e32 v34, 0xffff, v56
	s_and_saveexec_b64 s[0:1], s[4:5]
	v_lshlrev_b32_e32 v34, 16, v34
	v_sub_f32_e32 v34, v35, v34
	v_cvt_pk_bf16_f32 v34, v34, 0
	s_or_b64 exec, exec, s[0:1]
	v_cvt_pk_bf16_f32 v57, v36, 0
	v_and_b32_e32 v35, 0xffff, v57
	s_and_saveexec_b64 s[0:1], s[4:5]
	v_lshlrev_b32_e32 v35, 16, v35
	v_sub_f32_e32 v35, v36, v35
	v_cvt_pk_bf16_f32 v35, v35, 0
	s_or_b64 exec, exec, s[0:1]
	v_cvt_pk_bf16_f32 v54, v37, 0
	s_mov_b32 s3, 0x5040100
	v_and_b32_e32 v36, 0xffff, v54
	v_perm_b32 v52, v52, v51, s3
	v_perm_b32 v53, v55, v53, s3
	v_perm_b32 v51, v57, v56, s3
	s_and_saveexec_b64 s[0:1], s[4:5]
	v_lshlrev_b32_e32 v36, 16, v36
	v_sub_f32_e32 v36, v37, v36
	v_mov_b32_e32 v45, 0
	v_cvt_pk_bf16_f32 v36, v36, 0
	v_mov_b32_e32 v52, 0
	v_mov_b32_e32 v53, 0
	v_mov_b32_e32 v51, 0
	s_or_b64 exec, exec, s[0:1]
	v_perm_b32 v37, v36, v35, s3
	v_perm_b32 v36, v34, v41, s3
	v_perm_b32 v35, v40, v39, s3
	v_perm_b32 v34, v38, v50, s3
	v_cndmask_b32_e32 v41, 0, v54, vcc
	v_perm_b32 v38, v52, v45, s3
	v_alignbit_b32 v39, v53, v52, 16
	v_alignbit_b32 v40, v51, v53, 16
	v_alignbit_b32 v41, v41, v51, 16
	v_mfma_f32_16x16x32_bf16 v[30:33], v[34:37], v[30:33], 0
	s_mov_b32 s0, 0xbfb8aa3b
	v_bfe_u32 v53, v1, 3, 1
	v_cmp_eq_u32_e32 vcc, 0, v53
	v_mfma_f32_16x16x32_bf16 v[26:29], v[38:41], v[26:29], v[30:33]
	v_lshlrev_b32_e32 v54, 2, v1
	v_mov_b32_e32 v50, s44
	v_mov_b32_e32 v51, 0
	s_nop 0
	v_mov_b32_e32 v33, s45
	v_mfma_f32_16x16x32_bf16 v[22:25], v[34:37], v[22:25], 0
	s_nop 1
	v_add_f32_e32 v30, v49, v26
	v_mul_f32_e64 v26, |v30|, s0
	v_exp_f32_e32 v31, v26
	v_add_f32_e32 v32, v49, v27
	v_min_f32_e32 v27, 0, v30
	v_mul_f32_e64 v30, |v32|, s0
; #define LAS __attribute__((address_space(3)))
; __device__ __forceinline__ unsigned f2bf(float f) { return pk2(f, 0.f) & 0xffffu; }
; #define MFMA16(a, b, c) __builtin_amdgcn_mfma_f32_16x16x32_bf16((a), (b), (c), 0, 0, 0)
; __device__ __forceinline__ void gate_half_item(LAS unsigned char* lds, int tb, const bf16* H, const bf16* Win_t, bf16* GT, float* DTt, float* At, const float* bg_f, const float* bg_b, ...
;     ...
;                 for (int rt = 0; rt < 2; ++rt) { bf16x8 A1, A2;
;                     { const LAS f32x4* lp = (const LAS f32x4*)(LR + (16 * rt + lr_g) * 32 + 16 * d + ((8 * lq_g) & 15)); const f32x4 l0 = lp[0], l1 = lp[1]; const float lv[8] = {l0.x, l0.y, l0.z, l0.w, l1.x, l1.y, l1.z, l1.w};
; #pragma unroll
;                       for (int e = 0; e < 8; ++e) { const unsigned hi = f2bf(lv[e]); const float rem = lv[e] - __builtin_bit_cast(float, hi << 16);
;                           A1[e] = (lq_g < 2) ? (short)hi : (short)f2bf(rem); A2[e] = (lq_g < 2) ? (short)hi : (short)0; } }
; #pragma unroll
;                     for (int c4 = 0; c4 < 4; ++c4) { pg8::f32x4 acc = {0.f, 0.f, 0.f, 0.f}; acc = MFMA16(A1, B1[c4], acc); acc = MFMA16(A2, B2[c4], acc);
;                         const int colc = 16 * (4 * (wave & 3) + c4) + lr_g;
; #pragma unroll
;                         for (int r = 0; r < 4; ++r) { const float dot = acc[r] + bgc[c4];
;                             Gd[(size_t)(tb + 16 * rt + 4 * lq_g + r) * 256 + colc] = (bf16)f2bf((fminf(dot, 0.f) - 0.69314718056f * __builtin_amdgcn_logf(1.0f + __builtin_amdgcn_exp2f(-1.44269504089f * fabsf(dot)))) * (1.0f / 16.0f)); } } }
;                 { const int tok = tid >> 4, dh = tid & 15, dd = dh >> 3, hh = dh & 7; const size_t m = tb + tok;
;                     const float raw = DTR[tok * 16 + dh] + (dd ? dt_bias_b : dt_bias_f)[hh]; const float dt = fmaxf(raw, 0.f) + 0.69314718056f * __builtin_amdgcn_logf(1.0f + __builtin_amdgcn_exp2f(-1.44269504089f * fabsf(raw)));
;                     DTt[((size_t)dd * MALL + m) * 8 + hh] = dt; At[((size_t)dd * MALL + m) * 8 + hh] = -dt * __expf((dd ? a_log_b : a_log_f)[hh]); }
	v_add_f32_e32 v31, 1.0, v31
	v_log_f32_e32 v31, v31
	v_exp_f32_e32 v30, v30
	v_or_b32_e32 v26, 16, v44
	v_add_f32_e32 v28, v49, v28
	v_fmac_f32_e32 v27, 0xbf317218, v31
	v_mul_f32_e32 v27, 0x3d800000, v27
	v_add_f32_e32 v30, 1.0, v30
	v_cvt_pk_bf16_f32 v31, v27, s0
	v_ashrrev_i32_e32 v27, 31, v26
	v_log_f32_e32 v30, v30
	v_lshlrev_b64 v[26:27], 9, v[26:27]
	v_lshl_add_u64 v[26:27], v[42:43], 0, v[26:27]
	global_store_short v[26:27], v31, off
	v_min_f32_e32 v31, 0, v32
	v_fmac_f32_e32 v31, 0xbf317218, v30
	v_mul_f32_e32 v30, 0x3d800000, v31
	v_cvt_pk_bf16_f32 v45, v30, s0
	v_mul_f32_e64 v30, |v28|, s0
	v_exp_f32_e32 v32, v30
	v_mfma_f32_16x16x32_bf16 v[18:21], v[38:41], v[18:21], v[22:25]
	v_or_b32_e32 v30, 17, v44
	v_min_f32_e32 v28, 0, v28
	v_add_f32_e32 v52, 1.0, v32
	v_mov_b32_e32 v32, s47
	v_cndmask_b32_e32 v33, v32, v33, vcc
	v_mov_b32_e32 v32, s46
	v_cndmask_b32_e32 v32, v32, v50, vcc
	v_and_b32_e32 v50, 28, v54
	v_lshl_add_u64 v[32:33], v[32:33], 0, v[50:51]
	global_load_dword v55, v[32:33], off
	v_add_f32_e32 v18, v48, v18
	v_mul_f32_e64 v22, |v18|, s0
	v_exp_f32_e32 v24, v22
	v_add_f32_e32 v19, v48, v19
	v_mul_f32_e64 v25, |v19|, s0
	v_exp_f32_e32 v25, v25
	v_add_f32_e32 v24, 1.0, v24
	v_log_f32_e32 v24, v24
	v_min_f32_e32 v18, 0, v18
	v_log_f32_e32 v32, v52
	v_ashrrev_i32_e32 v31, 31, v30
	v_fmac_f32_e32 v18, 0xbf317218, v24
	v_mul_f32_e32 v18, 0x3d800000, v18
	v_add_f32_e32 v24, 1.0, v25
	v_log_f32_e32 v24, v24
	v_cvt_pk_bf16_f32 v18, v18, s0
	global_store_short v[26:27], v18, off offset:32
	v_min_f32_e32 v18, 0, v19
	v_add_f32_e32 v19, v48, v20
	v_mul_f32_e64 v20, |v19|, s0
	v_fmac_f32_e32 v28, 0xbf317218, v32
	v_exp_f32_e32 v20, v20
	v_lshlrev_b64 v[30:31], 9, v[30:31]
	v_mul_f32_e32 v28, 0x3d800000, v28
	v_add_f32_e32 v33, v49, v29
	v_fmac_f32_e32 v18, 0xbf317218, v24
	v_lshl_add_u64 v[30:31], v[42:43], 0, v[30:31]
	v_cvt_pk_bf16_f32 v32, v28, s0
	v_mul_f32_e64 v28, |v33|, s0
	v_mul_f32_e32 v18, 0x3d800000, v18
	global_store_short v[30:31], v45, off
	v_exp_f32_e32 v45, v28
	v_cvt_pk_bf16_f32 v18, v18, s0
	global_store_short v[30:31], v18, off offset:32
	v_add_f32_e32 v18, 1.0, v20
	v_add_f32_e32 v20, v48, v21
	v_log_f32_e32 v18, v18
	v_mul_f32_e64 v21, |v20|, s0
	v_exp_f32_e32 v21, v21
	v_or_b32_e32 v28, 18, v44
	v_add_f32_e32 v45, 1.0, v45
	v_ashrrev_i32_e32 v29, 31, v28
	v_log_f32_e32 v45, v45
	v_min_f32_e32 v19, 0, v19
	v_lshlrev_b64 v[28:29], 9, v[28:29]
	v_fmac_f32_e32 v19, 0xbf317218, v18
	v_lshl_add_u64 v[28:29], v[42:43], 0, v[28:29]
	v_mul_f32_e32 v18, 0x3d800000, v19
	v_add_f32_e32 v19, 1.0, v21
	global_store_short v[28:29], v32, off
	v_min_f32_e32 v32, 0, v33
	v_log_f32_e32 v19, v19
	v_fmac_f32_e32 v32, 0xbf317218, v45
	v_mul_f32_e32 v32, 0x3d800000, v32
	v_cvt_pk_bf16_f32 v18, v18, s0
	v_cvt_pk_bf16_f32 v45, v32, s0
	v_or_b32_e32 v32, 19, v44
	global_store_short v[28:29], v18, off offset:32
	v_min_f32_e32 v18, 0, v20
	v_ashrrev_i32_e32 v33, 31, v32
	v_fmac_f32_e32 v18, 0xbf317218, v19
	v_lshlrev_b64 v[22:23], 9, v[32:33]
	v_mul_f32_e32 v18, 0x3d800000, v18
	v_lshl_add_u64 v[22:23], v[42:43], 0, v[22:23]
	v_cvt_pk_bf16_f32 v18, v18, s0
	global_store_short v[22:23], v18, off offset:32
	v_add_u32_e32 v18, 0, v54
	ds_read_b32 v18, v18 offset:53248
	v_mfma_f32_16x16x32_bf16 v[14:17], v[34:37], v[14:17], 0
	v_ashrrev_i32_e32 v1, 4, v1
	s_add_u32 s14, s78, 0xa00000
	s_addc_u32 s15, s79, 0
	v_mfma_f32_16x16x32_bf16 v[10:13], v[38:41], v[10:13], v[14:17]
	v_mov_b32_e32 v19, s40
	s_add_u32 s22, s78, 0xb10000
	s_addc_u32 s23, s79, 0
	v_mfma_f32_16x16x32_bf16 v[6:9], v[34:37], v[6:9], 0
	global_store_short v[22:23], v45, off
	s_nop 2
	v_add_f32_e32 v10, v47, v10
	s_waitcnt vmcnt(7) lgkmcnt(0)
	v_add_f32_e32 v16, v18, v55
	v_mul_f32_e64 v14, |v16|, s0
	v_exp_f32_e32 v14, v14
	v_mul_f32_e64 v15, |v10|, s0
	v_exp_f32_e32 v18, v15
	v_add_f32_e32 v11, v47, v11
	v_add_f32_e32 v14, 1.0, v14
	v_log_f32_e32 v17, v14
	v_add_u32_e32 v14, s19, v1
	v_max_f32_e32 v1, 0, v16
	v_ashrrev_i32_e32 v15, 31, v14
	v_fmamk_f32 v1, v17, 0x3f317218, v1
	v_mul_u32_u24_e32 v16, 0x4400, v53
	v_mov_b32_e32 v17, v51
	v_lshl_add_u64 v[14:15], v[16:17], 0, v[14:15]
	v_lshlrev_b64 v[14:15], 5, v[14:15]
	v_or_b32_e32 v14, v14, v50
	v_lshl_add_u64 v[16:17], s[14:15], 0, v[14:15]
	global_store_dword v[16:17], v1, off
	v_mov_b32_e32 v16, s43
	v_mov_b32_e32 v17, s41
	v_cndmask_b32_e32 v17, v16, v17, vcc
	v_mov_b32_e32 v16, s42
	v_cndmask_b32_e32 v16, v16, v19, vcc
	v_lshl_add_u64 v[16:17], v[16:17], 0, v[50:51]
	global_load_dword v16, v[16:17], off
	v_add_f32_e32 v17, 1.0, v18
	v_log_f32_e32 v17, v17
	v_mul_f32_e64 v18, |v11|, s0
	v_exp_f32_e32 v18, v18
	v_min_f32_e32 v10, 0, v10
	v_fmac_f32_e32 v10, 0xbf317218, v17
	v_mul_f32_e32 v10, 0x3d800000, v10
	v_add_f32_e32 v17, 1.0, v18
	v_log_f32_e32 v17, v17
	v_cvt_pk_bf16_f32 v10, v10, s0
	global_store_short v[26:27], v10, off offset:64
	v_min_f32_e32 v10, 0, v11
	v_add_f32_e32 v11, v47, v12
	v_mul_f32_e64 v12, |v11|, s0
	v_exp_f32_e32 v12, v12
	v_fmac_f32_e32 v10, 0xbf317218, v17
	v_mul_f32_e32 v10, 0x3d800000, v10
	v_cvt_pk_bf16_f32 v10, v10, s0
	global_store_short v[30:31], v10, off offset:64
	v_min_f32_e32 v10, 0, v11
	v_add_f32_e32 v11, 1.0, v12
	v_add_f32_e32 v12, v47, v13
	v_mul_f32_e64 v13, |v12|, s0
	v_log_f32_e32 v11, v11
	v_exp_f32_e32 v13, v13
	v_mfma_f32_16x16x32_bf16 v[2:5], v[38:41], v[2:5], v[6:9]
	s_or_b32 s6, s19, 32
	v_fmac_f32_e32 v10, 0xbf317218, v11
	v_add_f32_e32 v11, 1.0, v13
	v_log_f32_e32 v11, v11
	v_mul_f32_e32 v10, 0x3d800000, v10
	s_nop 2
	v_add_f32_e32 v2, v46, v2
	v_mul_f32_e64 v6, |v2|, s0
	v_cvt_pk_bf16_f32 v10, v10, s0
	v_exp_f32_e32 v6, v6
	global_store_short v[28:29], v10, off offset:64
	v_min_f32_e32 v10, 0, v12
	v_fmac_f32_e32 v10, 0xbf317218, v11
	v_mul_f32_e32 v7, 0x3d800000, v10
	v_cvt_pk_bf16_f32 v7, v7, s0
	v_add_f32_e32 v6, 1.0, v6
	v_add_f32_e32 v3, v46, v3
	global_store_short v[22:23], v7, off offset:64
	v_log_f32_e32 v6, v6
	v_mul_f32_e64 v7, |v3|, s0
	v_exp_f32_e32 v7, v7
	v_min_f32_e32 v2, 0, v2
	v_fmac_f32_e32 v2, 0xbf317218, v6
	v_mul_f32_e32 v2, 0x3d800000, v2
	v_add_f32_e32 v6, 1.0, v7
	v_log_f32_e32 v6, v6
	v_cvt_pk_bf16_f32 v2, v2, s0
	global_store_short v[26:27], v2, off offset:96
	v_min_f32_e32 v2, 0, v3
	v_add_f32_e32 v3, v46, v4
	v_mul_f32_e64 v4, |v3|, s0
	v_exp_f32_e32 v4, v4
	v_fmac_f32_e32 v2, 0xbf317218, v6
	v_mul_f32_e32 v2, 0x3d800000, v2
	v_cvt_pk_bf16_f32 v2, v2, s0
	global_store_short v[30:31], v2, off offset:96
	v_add_f32_e32 v2, 1.0, v4
	v_add_f32_e32 v4, v46, v5
	v_log_f32_e32 v2, v2
	v_mul_f32_e64 v5, |v4|, s0
	v_exp_f32_e32 v5, v5
	v_min_f32_e32 v3, 0, v3
	v_fmac_f32_e32 v3, 0xbf317218, v2
	v_mul_f32_e32 v2, 0x3d800000, v3
	v_add_f32_e32 v3, 1.0, v5
	v_log_f32_e32 v3, v3
	v_cvt_pk_bf16_f32 v2, v2, s0
	global_store_short v[28:29], v2, off offset:96
	v_min_f32_e32 v2, 0, v4
	v_fmac_f32_e32 v2, 0xbf317218, v3
	v_mul_f32_e32 v2, 0x3d800000, v2
	v_cvt_pk_bf16_f32 v2, v2, s0
	global_store_short v[22:23], v2, off offset:96
	s_waitcnt vmcnt(8)
; #define LAS __attribute__((address_space(3)))
; __device__ __forceinline__ void gate_half_item(LAS unsigned char* lds, int tb, const bf16* H, const bf16* Win_t, bf16* GT, float* DTt, float* At, const float* bg_f, const float* bg_b, ...
;     int tid_o_ = threadIdx.x; asm volatile("" : "+v"(tid_o_)); const int tid = tid_o_, lane = tid & 63, wave = __builtin_amdgcn_readfirstlane(tid >> 6);
;                 LAS float* PART = (LAS float*)lds; LAS float* LR = (LAS float*)(lds + 49152); LAS float* DTR = (LAS float*)(lds + 53248);
;                 {
;                     const int lr_ = lane & 15, lq_ = lane >> 4; pg8::f32x4 acc[2][3];
; #pragma unroll
;                     for (int rt = 0; rt < 2; ++rt)
; #pragma unroll
;                         for (int ct = 0; ct < 3; ++ct) acc[rt][ct] = (pg8::f32x4){0.f, 0.f, 0.f, 0.f};
;                     const bf16* hp = H + (size_t)(tb + lr_) * D + 128 * wave + 8 * lq_; const bf16* wp = Win_t + (size_t)(2816 + lr_) * D + 128 * wave + 8 * lq_;
;                     bf16x8 af[4][2], bfr[4][3];
; #pragma unroll
;                     for (int ks = 0; ks < 4; ++ks) {
; #pragma unroll
;                         for (int rt = 0; rt < 2; ++rt) af[ks][rt] = *(const bf16x8*)(hp + (size_t)(16 * rt) * D + 32 * ks);
; #pragma unroll
;                         for (int ct = 0; ct < 3; ++ct) bfr[ks][ct] = *(const bf16x8*)(wp + (size_t)(16 * ct) * D + 32 * ks); }
; #pragma unroll
;                     for (int ks = 0; ks < 4; ++ks)
; #pragma unroll
;                         for (int rt = 0; rt < 2; ++rt)
; #pragma unroll
;                             for (int ct = 0; ct < 3; ++ct) acc[rt][ct] = MFMA16(af[ks][rt], bfr[ks][ct], acc[rt][ct]);
; #pragma unroll
;                     for (int rt = 0; rt < 2; ++rt)
; #pragma unroll
;                         for (int ct = 0; ct < 3; ++ct)
; #pragma unroll
;                             for (int r = 0; r < 4; ++r) PART[(wave * 32 + 16 * rt + 4 * lq_ + r) * 48 + 16 * ct + lr_] = acc[rt][ct][r];
;                 }
;                 const int d = wave >> 2, lr_g = lane & 15, lq_g = lane >> 4; bf16* Gd = GT + (size_t)d * MALL * 256;
;                 bf16x8 B1[4], B2[4]; float bgc[4];
; #pragma unroll
;                 for (int c4 = 0; c4 < 4; ++c4) { bgc[c4] = (d ? bg_b : bg_f)[16 * (4 * (wave & 3) + c4) + lr_g];
	v_mul_f32_e32 v3, 0x3fb8aa3b, v16
	v_exp_f32_e32 v3, v3
	s_nop 0
	v_mul_f32_e64 v1, v3, -v1
	v_lshl_add_u64 v[2:3], s[22:23], 0, v[14:15]
	global_store_dword v[2:3], v1, off
	v_mov_b32_e32 v1, v0
	s_barrier
	s_nop 0
	v_readfirstlane_b32 s4, v1
	v_and_b32_e32 v34, 15, v1
	s_ashr_i32 s3, s4, 6
	v_or_b32_e32 v2, s6, v34
	v_ashrrev_i32_e32 v3, 31, v2
	s_lshl_b32 s0, s3, 7
	v_lshlrev_b64 v[2:3], 11, v[2:3]
	s_ashr_i32 s1, s0, 31
	v_lshl_add_u64 v[2:3], s[76:77], 0, v[2:3]
	s_lshl_b64 s[0:1], s[0:1], 1
	v_lshl_add_u64 v[2:3], v[2:3], 0, s[0:1]
	v_and_b32_e32 v50, 48, v1
	v_lshl_add_u64 v[64:65], v[2:3], 0, v[50:51]
	v_lshlrev_b32_e32 v2, 11, v34
	v_mov_b32_e32 v3, v51
	v_lshl_add_u64 v[2:3], s[8:9], 0, v[2:3]
	v_lshl_add_u64 v[2:3], v[2:3], 0, s[0:1]
	v_lshl_add_u64 v[44:45], v[2:3], 0, v[50:51]
	s_mov_b32 s0, 0x580000
	v_add_co_u32_e32 v6, vcc, s0, v44
	s_mov_b32 s0, 0x588000
	s_nop 0
	v_addc_co_u32_e32 v7, vcc, 0, v45, vcc
	v_add_co_u32_e32 v52, vcc, s0, v44
	s_nop 1
	v_addc_co_u32_e32 v53, vcc, 0, v45, vcc
	s_mov_b32 s0, 0x590000
	v_add_co_u32_e32 v66, vcc, s0, v44
	s_mov_b32 s0, 0x8000
	s_nop 0
	s_nop 1
	v_addc_co_u32_e32 v67, vcc, 0, v45, vcc
	v_add_co_u32_e32 v68, vcc, s0, v64
	s_nop 0
	s_nop 1
	v_addc_co_u32_e32 v69, vcc, 0, v65, vcc
	s_mov_b64 s[0:1], 0x580000
	v_lshl_add_u64 v[70:71], v[44:45], 0, s[0:1]
	s_cmpk_lt_u32 s4, 0x100
	s_cselect_b32 s1, s65, s37
	s_cselect_b32 s0, s64, s36
	s_and_b32 s5, s4, 0xc0
	v_bfe_u32 v35, v1, 4, 2
	global_load_dwordx4 v[148:151], v[64:65], off
	global_load_dwordx4 v[152:155], v[64:65], off offset:64
	global_load_dwordx4 v[156:159], v[64:65], off offset:128
	global_load_dwordx4 v[160:163], v[64:65], off offset:192
	global_load_dwordx4 v[164:167], v[68:69], off
	global_load_dwordx4 v[168:171], v[68:69], off offset:64
	global_load_dwordx4 v[172:175], v[68:69], off offset:128
	global_load_dwordx4 v[176:179], v[68:69], off offset:192
	global_load_dwordx4 v[180:183], v[70:71], off
	global_load_dwordx4 v[184:187], v[70:71], off offset:64
	global_load_dwordx4 v[188:191], v[70:71], off offset:128
	global_load_dwordx4 v[192:195], v[70:71], off offset:192
	global_load_dwordx4 v[196:199], v[52:53], off
	global_load_dwordx4 v[200:203], v[52:53], off offset:64
	global_load_dwordx4 v[204:207], v[52:53], off offset:128
	global_load_dwordx4 v[208:211], v[52:53], off offset:192
	global_load_dwordx4 v[212:215], v[66:67], off
	global_load_dwordx4 v[216:219], v[66:67], off offset:64
	global_load_dwordx4 v[220:223], v[66:67], off offset:128
	global_load_dwordx4 v[224:227], v[66:67], off offset:192
	v_or_b32_e32 v42, s5, v34
	v_lshlrev_b32_e32 v43, 2, v35
	v_and_b32_e32 v44, 63, v1
	s_waitcnt vmcnt(0)
	v_mfma_f32_16x16x32_bf16 v[18:21], v[148:151], v[180:183], 0
	v_mfma_f32_16x16x32_bf16 v[26:29], v[148:151], v[196:199], 0
	v_mfma_f32_16x16x32_bf16 v[2:5], v[148:151], v[212:215], 0
	v_mfma_f32_16x16x32_bf16 v[6:9], v[164:167], v[180:183], 0
	v_mfma_f32_16x16x32_bf16 v[10:13], v[164:167], v[196:199], 0
	v_mfma_f32_16x16x32_bf16 v[14:17], v[164:167], v[212:215], 0
	v_mfma_f32_16x16x32_bf16 v[18:21], v[152:155], v[184:187], v[18:21]
	v_mfma_f32_16x16x32_bf16 v[26:29], v[152:155], v[200:203], v[26:29]
	v_mfma_f32_16x16x32_bf16 v[2:5], v[152:155], v[216:219], v[2:5]
	v_mfma_f32_16x16x32_bf16 v[6:9], v[168:171], v[184:187], v[6:9]
	v_mfma_f32_16x16x32_bf16 v[10:13], v[168:171], v[200:203], v[10:13]
	v_mfma_f32_16x16x32_bf16 v[14:17], v[168:171], v[216:219], v[14:17]
	v_mfma_f32_16x16x32_bf16 v[18:21], v[156:159], v[188:191], v[18:21]
	v_mfma_f32_16x16x32_bf16 v[26:29], v[156:159], v[204:207], v[26:29]
	v_mfma_f32_16x16x32_bf16 v[2:5], v[156:159], v[220:223], v[2:5]
	v_mfma_f32_16x16x32_bf16 v[6:9], v[172:175], v[188:191], v[6:9]
	v_mfma_f32_16x16x32_bf16 v[10:13], v[172:175], v[204:207], v[10:13]
	v_mfma_f32_16x16x32_bf16 v[14:17], v[172:175], v[220:223], v[14:17]
	v_mfma_f32_16x16x32_bf16 v[18:21], v[160:163], v[192:195], v[18:21]
	v_mfma_f32_16x16x32_bf16 v[26:29], v[160:163], v[208:211], v[26:29]
	v_mfma_f32_16x16x32_bf16 v[2:5], v[160:163], v[224:227], v[2:5]
	v_mfma_f32_16x16x32_bf16 v[6:9], v[176:179], v[192:195], v[6:9]
	v_mfma_f32_16x16x32_bf16 v[10:13], v[176:179], v[208:211], v[10:13]
	v_mfma_f32_16x16x32_bf16 v[14:17], v[176:179], v[224:227], v[14:17]
	s_nop 7
	s_nop 1
	v_lshlrev_b32_e32 v22, 2, v42
	global_load_dword v49, v22, s[0:1]
	global_load_dword v48, v22, s[0:1] offset:64
	global_load_dword v47, v22, s[0:1] offset:128
	global_load_dword v46, v22, s[0:1] offset:192
	v_lshl_or_b32 v22, s3, 5, v43
	s_movk_i32 s0, 0xc0
	v_lshlrev_b32_e32 v23, 2, v34
	v_mul_lo_u32 v22, v22, s0
	v_add3_u32 v22, 0, v23, v22
	s_lshl_b32 s1, s3, 13
	s_add_i32 s1, s1, 0
	ds_write2_b32 v22, v18, v26 offset1:16
	ds_write2_b32 v22, v20, v28 offset0:96 offset1:112
	s_nop 5
	ds_write2_b32 v22, v2, v19 offset0:32 offset1:48
	ds_write2_b32 v22, v27, v3 offset0:64 offset1:80
	ds_write2_b32 v22, v4, v21 offset0:128 offset1:144
	ds_write2_b32 v22, v29, v5 offset0:160 offset1:176
	v_add_u32_e32 v2, 0xc00, v22
	ds_write2_b32 v2, v6, v10 offset1:16
	ds_write2_b32 v2, v8, v12 offset0:96 offset1:112
	s_nop 5
	ds_write2_b32 v2, v14, v7 offset0:32 offset1:48
	ds_write2_b32 v2, v11, v15 offset0:64 offset1:80
	ds_write2_b32 v2, v16, v9 offset0:128 offset1:144
	ds_write2_b32 v2, v13, v17 offset0:160 offset1:176
	v_lshl_add_u32 v2, v44, 4, s1
	s_mov_b32 s1, 0x2aaaaaab
	v_mul_hi_i32 v36, v1, s1
	v_lshrrev_b32_e32 v37, 31, v36
	v_ashrrev_i32_e32 v36, 3, v36
	v_add_u32_e32 v36, v36, v37
	v_mul_lo_u32 v37, v36, 48
	v_sub_u32_e32 v45, v1, v37
	v_lshlrev_b32_e32 v37, 2, v45
	v_mul_lo_u32 v38, v36, s0
	v_add_u32_e32 v2, 0x10000, v2
	v_add3_u32 v52, 0, v37, v38
	ds_read_b128 v[30:33], v2
	ds_read_b128 v[26:29], v2 offset:1024
	ds_read_b128 v[22:25], v2 offset:2048
	ds_read_b128 v[18:21], v2 offset:3072
	ds_read_b128 v[14:17], v2 offset:4096
	ds_read_b128 v[10:13], v2 offset:5120
	ds_read_b128 v[6:9], v2 offset:6144
	ds_read_b128 v[2:5], v2 offset:7168
	s_waitcnt lgkmcnt(0)
	s_barrier
; #define LAS __attribute__((address_space(3)))
; __device__ __forceinline__ unsigned f2bf(float f) { return pk2(f, 0.f) & 0xffffu; }
; #define MFMA16(a, b, c) __builtin_amdgcn_mfma_f32_16x16x32_bf16((a), (b), (c), 0, 0, 0)
; __device__ __forceinline__ void gate_half_item(LAS unsigned char* lds, int tb, const bf16* H, const bf16* Win_t, bf16* GT, float* DTt, float* At, const float* bg_f, const float* bg_b, ...
;     ...
;                 __syncthreads();
; #pragma unroll
;                 for (int i = 0; i < 3; ++i) { const int idx = tid + NT * i, tok = idx / 48, col2 = idx % 48; float v = 0.f;
; #pragma unroll
;                     for (int w8 = 0; w8 < 8; ++w8) v += PART[(w8 * 32 + tok) * 48 + col2];
;                     if (col2 < 32) LR[tok * 32 + col2] = v; else DTR[tok * 16 + col2 - 32] = v; }
;                 __syncthreads();
; #pragma unroll
;                 for (int rt = 0; rt < 2; ++rt) { bf16x8 A1, A2;
;                     { const LAS f32x4* lp = (const LAS f32x4*)(LR + (16 * rt + lr_g) * 32 + 16 * d + ((8 * lq_g) & 15)); const f32x4 l0 = lp[0], l1 = lp[1]; const float lv[8] = {l0.x, l0.y, l0.z, l0.w, l1.x, l1.y, l1.z, l1.w};
; #pragma unroll
;                       for (int e = 0; e < 8; ++e) { const unsigned hi = f2bf(lv[e]); const float rem = lv[e] - __builtin_bit_cast(float, hi << 16);
;                           A1[e] = (lq_g < 2) ? (short)hi : (short)f2bf(rem); A2[e] = (lq_g < 2) ? (short)hi : (short)0; } }
; #pragma unroll
;                     for (int c4 = 0; c4 < 4; ++c4) { pg8::f32x4 acc = {0.f, 0.f, 0.f, 0.f}; acc = MFMA16(A1, B1[c4], acc); acc = MFMA16(A2, B2[c4], acc);
	ds_read2st64_b32 v[38:39], v52 offset1:24
	ds_read2st64_b32 v[40:41], v52 offset0:48 offset1:72
	ds_read2st64_b32 v[50:51], v52 offset0:96 offset1:120
	v_cmp_lt_i32_e32 vcc, 31, v45
	s_waitcnt lgkmcnt(2)
	v_add_f32_e32 v38, 0, v38
	v_add_f32_e32 v53, v38, v39
	ds_read2st64_b32 v[38:39], v52 offset0:144 offset1:168
	s_waitcnt lgkmcnt(2)
	v_add_f32_e32 v40, v53, v40
	v_add_f32_e32 v40, v40, v41
	s_waitcnt lgkmcnt(1)
	v_add_f32_e32 v40, v40, v50
	v_add_f32_e32 v40, v40, v51
	s_waitcnt lgkmcnt(0)
	v_add_f32_e32 v38, v40, v38
	v_add_f32_e32 v38, v38, v39
	s_and_saveexec_b64 s[0:1], vcc
	s_xor_b64 s[0:1], exec, s[0:1]
	v_lshlrev_b32_e32 v36, 6, v36
	v_add3_u32 v36, 0, v36, v37
	ds_write_b32 v36, v38 offset:53120
	s_andn2_saveexec_b64 s[0:1], s[0:1]
	v_lshlrev_b32_e32 v36, 7, v36
	v_add3_u32 v36, 0, v36, v37
	ds_write_b32 v36, v38 offset:49152
	s_or_b64 exec, exec, s[0:1]
	v_add_u32_e32 v37, 0x200, v1
	s_mov_b32 s0, 0x2aaaaaab
	v_mul_hi_i32 v36, v37, s0
	v_lshrrev_b32_e32 v38, 31, v36
	v_ashrrev_i32_e32 v36, 3, v36
	v_add_u32_e32 v36, v36, v38
	v_mul_lo_u32 v38, v36, 48
	v_sub_u32_e32 v45, v37, v38
	s_movk_i32 s0, 0xc0
	v_lshlrev_b32_e32 v37, 2, v45
	v_mul_lo_u32 v38, v36, s0
	v_add3_u32 v52, 0, v37, v38
	ds_read2st64_b32 v[38:39], v52 offset1:24
	ds_read2st64_b32 v[40:41], v52 offset0:48 offset1:72
	ds_read2st64_b32 v[50:51], v52 offset0:96 offset1:120
	v_cmp_lt_i32_e32 vcc, 31, v45
	s_waitcnt lgkmcnt(2)
	v_add_f32_e32 v38, 0, v38
	v_add_f32_e32 v53, v38, v39
	ds_read2st64_b32 v[38:39], v52 offset0:144 offset1:168
	s_waitcnt lgkmcnt(2)
	v_add_f32_e32 v40, v53, v40
	v_add_f32_e32 v40, v40, v41
	s_waitcnt lgkmcnt(1)
	v_add_f32_e32 v40, v40, v50
	v_add_f32_e32 v40, v40, v51
	s_waitcnt lgkmcnt(0)
	v_add_f32_e32 v38, v40, v38
	v_add_f32_e32 v38, v38, v39
	s_and_saveexec_b64 s[0:1], vcc
	s_xor_b64 s[0:1], exec, s[0:1]
	v_lshlrev_b32_e32 v36, 6, v36
	v_add3_u32 v36, 0, v36, v37
	ds_write_b32 v36, v38 offset:53120
	s_andn2_saveexec_b64 s[0:1], s[0:1]
	v_lshlrev_b32_e32 v36, 7, v36
	v_add3_u32 v36, 0, v36, v37
	ds_write_b32 v36, v38 offset:49152
	s_or_b64 exec, exec, s[0:1]
	v_add_u32_e32 v37, 0x400, v1
	s_mov_b32 s0, 0x2aaaaaab
	v_mul_hi_i32 v36, v37, s0
	v_lshrrev_b32_e32 v38, 31, v36
	v_ashrrev_i32_e32 v36, 3, v36
	v_add_u32_e32 v36, v36, v38
	v_mul_lo_u32 v38, v36, 48
	v_sub_u32_e32 v45, v37, v38
	s_movk_i32 s0, 0xc0
	v_lshlrev_b32_e32 v37, 2, v45
	v_mul_lo_u32 v38, v36, s0
	v_add3_u32 v52, 0, v37, v38
	ds_read2st64_b32 v[38:39], v52 offset1:24
	ds_read2st64_b32 v[40:41], v52 offset0:48 offset1:72
	ds_read2st64_b32 v[50:51], v52 offset0:96 offset1:120
	v_cmp_lt_i32_e32 vcc, 31, v45
	s_waitcnt lgkmcnt(2)
	v_add_f32_e32 v38, 0, v38
	v_add_f32_e32 v53, v38, v39
	ds_read2st64_b32 v[38:39], v52 offset0:144 offset1:168
	s_waitcnt lgkmcnt(2)
	v_add_f32_e32 v40, v53, v40
	v_add_f32_e32 v40, v40, v41
	s_waitcnt lgkmcnt(1)
	v_add_f32_e32 v40, v40, v50
	v_add_f32_e32 v40, v40, v51
	s_waitcnt lgkmcnt(0)
	v_add_f32_e32 v38, v40, v38
	v_add_f32_e32 v38, v38, v39
	s_and_saveexec_b64 s[0:1], vcc
	s_xor_b64 s[0:1], exec, s[0:1]
	v_lshlrev_b32_e32 v36, 6, v36
	v_add3_u32 v36, 0, v36, v37
	ds_write_b32 v36, v38 offset:53120
	s_or_saveexec_b64 s[0:1], s[0:1]
	v_lshlrev_b32_e32 v35, 3, v35
	s_xor_b64 exec, exec, s[0:1]
	v_lshlrev_b32_e32 v36, 7, v36
	v_add3_u32 v36, 0, v36, v37
	ds_write_b32 v36, v38 offset:49152
	s_or_b64 exec, exec, s[0:1]
	s_ashr_i32 s3, s4, 8
	s_lshl_b32 s0, s3, 6
	s_add_i32 s0, s0, 0
	v_and_b32_e32 v35, 8, v35
	v_lshl_add_u32 v35, v35, 2, s0
	v_lshlrev_b32_e32 v34, 7, v34
	v_add_u32_e32 v50, v35, v34
	s_waitcnt lgkmcnt(0)
	s_barrier
	ds_read_b128 v[38:41], v50 offset:49152
	ds_read_b128 v[34:37], v50 offset:49168
	v_cmp_gt_u32_e32 vcc, 32, v44
	v_cmp_lt_u32_e64 s[4:5], 31, v44
	s_waitcnt lgkmcnt(1)
	v_cvt_pk_bf16_f32 v45, v38, 0
	v_and_b32_e32 v44, 0xffff, v45
	s_and_saveexec_b64 s[0:1], s[4:5]
	v_lshlrev_b32_e32 v44, 16, v44
	v_sub_f32_e32 v38, v38, v44
	v_cvt_pk_bf16_f32 v44, v38, 0
	s_or_b64 exec, exec, s[0:1]
	v_cvt_pk_bf16_f32 v51, v39, 0
	v_and_b32_e32 v38, 0xffff, v51
	s_and_saveexec_b64 s[0:1], s[4:5]
	v_lshlrev_b32_e32 v38, 16, v38
	v_sub_f32_e32 v38, v39, v38
	v_cvt_pk_bf16_f32 v38, v38, 0
	s_or_b64 exec, exec, s[0:1]
	v_cvt_pk_bf16_f32 v52, v40, 0
	v_and_b32_e32 v39, 0xffff, v52
	s_and_saveexec_b64 s[0:1], s[4:5]
	v_lshlrev_b32_e32 v39, 16, v39
	v_sub_f32_e32 v39, v40, v39
	v_cvt_pk_bf16_f32 v39, v39, 0
	s_or_b64 exec, exec, s[0:1]
	v_cvt_pk_bf16_f32 v53, v41, 0
	v_and_b32_e32 v40, 0xffff, v53
	s_and_saveexec_b64 s[0:1], s[4:5]
	v_lshlrev_b32_e32 v40, 16, v40
	v_sub_f32_e32 v40, v41, v40
	v_cvt_pk_bf16_f32 v40, v40, 0
	s_or_b64 exec, exec, s[0:1]
	s_waitcnt lgkmcnt(0)
	v_cvt_pk_bf16_f32 v54, v34, 0
	v_and_b32_e32 v41, 0xffff, v54
	s_and_saveexec_b64 s[0:1], s[4:5]
	v_lshlrev_b32_e32 v41, 16, v41
	v_sub_f32_e32 v34, v34, v41
	v_cvt_pk_bf16_f32 v41, v34, 0
	s_or_b64 exec, exec, s[0:1]
	v_cvt_pk_bf16_f32 v55, v35, 0
	v_and_b32_e32 v34, 0xffff, v55
	s_and_saveexec_b64 s[0:1], s[4:5]
	v_lshlrev_b32_e32 v34, 16, v34
	v_sub_f32_e32 v34, v35, v34
	v_cvt_pk_bf16_f32 v34, v34, 0
	s_or_b64 exec, exec, s[0:1]
	v_cvt_pk_bf16_f32 v56, v36, 0
	v_and_b32_e32 v35, 0xffff, v56
	s_and_saveexec_b64 s[0:1], s[4:5]
	v_lshlrev_b32_e32 v35, 16, v35
	v_sub_f32_e32 v35, v36, v35
	v_cvt_pk_bf16_f32 v35, v35, 0
	s_or_b64 exec, exec, s[0:1]
	v_cvt_pk_bf16_f32 v36, v37, 0
	v_and_b32_e32 v57, 0xffff, v36
	s_and_saveexec_b64 s[0:1], s[4:5]
	v_lshlrev_b32_e32 v57, 16, v57
	v_sub_f32_e32 v37, v37, v57
	v_cvt_pk_bf16_f32 v57, v37, 0
	s_or_b64 exec, exec, s[0:1]
	s_mov_b32 s0, 0x5040100
	v_cndmask_b32_e32 v58, 0, v36, vcc
	v_perm_b32 v37, v57, v35, s0
	v_perm_b32 v36, v34, v41, s0
	v_perm_b32 v35, v40, v39, s0
	v_perm_b32 v34, v38, v44, s0
	v_cndmask_b32_e32 v45, 0, v45, vcc
	v_cndmask_b32_e32 v51, 0, v51, vcc
	v_cndmask_b32_e32 v52, 0, v52, vcc
	v_cndmask_b32_e32 v53, 0, v53, vcc
	v_cndmask_b32_e32 v54, 0, v54, vcc
	v_cndmask_b32_e32 v55, 0, v55, vcc
	v_cndmask_b32_e32 v56, 0, v56, vcc
	v_perm_b32 v41, v58, v56, s0
	v_perm_b32 v40, v55, v54, s0
	v_perm_b32 v39, v53, v52, s0
	v_perm_b32 v38, v51, v45, s0
	v_mfma_f32_16x16x32_bf16 v[52:55], v[34:37], v[30:33], 0
	s_mul_hi_i32 s1, s3, 0x880000
	s_mul_i32 s3, s3, 0x880000
	v_readlane_b32 s0, v240, 32
	v_mfma_f32_16x16x32_bf16 v[52:55], v[38:41], v[26:29], v[52:55]
	s_add_u32 s12, s0, s3
	s_mov_b32 s0, 0xbfb8aa3b
	v_readlane_b32 s3, v240, 33
	s_addc_u32 s13, s3, s1
	v_lshlrev_b32_e32 v42, 1, v42
	s_waitcnt vmcnt(3)
; __device__ __forceinline__ unsigned f2bf(float f) { return pk2(f, 0.f) & 0xffffu; }
; #define MFMA16(a, b, c) __builtin_amdgcn_mfma_f32_16x16x32_bf16((a), (b), (c), 0, 0, 0)
; __device__ __forceinline__ void gate_half_item(LAS unsigned char* lds, int tb, const bf16* H, const bf16* Win_t, bf16* GT, float* DTt, float* At, const float* bg_f, const float* bg_b, ...
;     ...
;                     for (int c4 = 0; c4 < 4; ++c4) { pg8::f32x4 acc = {0.f, 0.f, 0.f, 0.f}; acc = MFMA16(A1, B1[c4], acc); acc = MFMA16(A2, B2[c4], acc);
;                         const int colc = 16 * (4 * (wave & 3) + c4) + lr_g;
; #pragma unroll
;                         for (int r = 0; r < 4; ++r) { const float dot = acc[r] + bgc[c4];
;                             Gd[(size_t)(tb + 16 * rt + 4 * lq_g + r) * 256 + colc] = (bf16)f2bf((fminf(dot, 0.f) - 0.69314718056f * __builtin_amdgcn_logf(1.0f + __builtin_amdgcn_exp2f(-1.44269504089f * fabsf(dot)))) * (1.0f / 16.0f)); } } }
	s_nop 1
	v_add_f32_e32 v45, v49, v52
	v_mul_f32_e64 v44, |v45|, s0
	v_exp_f32_e32 v51, v44
	v_or_b32_e32 v44, s6, v43
	v_min_f32_e32 v45, 0, v45
	v_or_b32_e32 v62, 3, v44
	v_add_f32_e32 v43, 1.0, v51
	v_log_f32_e32 v51, v43
	v_mov_b32_e32 v43, 0
	v_lshl_add_u64 v[42:43], s[12:13], 0, v[42:43]
	v_ashrrev_i32_e32 v63, 31, v62
	v_fmac_f32_e32 v45, 0xbf317218, v51
	v_add_f32_e32 v51, v49, v53
	v_mul_f32_e64 v52, |v51|, s0
	v_exp_f32_e32 v56, v52
	v_mul_f32_e32 v45, 0x3d800000, v45
	v_cvt_pk_bf16_f32 v58, v45, s0
	v_ashrrev_i32_e32 v45, 31, v44
	v_lshlrev_b64 v[52:53], 9, v[44:45]
	v_add_f32_e32 v45, 1.0, v56
	v_log_f32_e32 v45, v45
	v_min_f32_e32 v51, 0, v51
	v_lshl_add_u64 v[56:57], v[42:43], 0, v[52:53]
	global_store_short v[56:57], v58, off
	v_fmac_f32_e32 v51, 0xbf317218, v45
	v_mul_f32_e32 v45, 0x3d800000, v51
	v_add_f32_e32 v51, v49, v54
	v_mul_f32_e64 v52, |v51|, s0
	v_exp_f32_e32 v54, v52
	v_or_b32_e32 v52, 1, v44
	v_ashrrev_i32_e32 v53, 31, v52
	v_lshlrev_b64 v[52:53], 9, v[52:53]
	v_add_f32_e32 v54, 1.0, v54
	v_log_f32_e32 v54, v54
	v_cvt_pk_bf16_f32 v45, v45, s0
	v_lshl_add_u64 v[58:59], v[42:43], 0, v[52:53]
	global_store_short v[58:59], v45, off
	v_min_f32_e32 v45, 0, v51
	v_add_f32_e32 v51, v49, v55
	v_mul_f32_e64 v52, |v51|, s0
	v_fmac_f32_e32 v45, 0xbf317218, v54
	v_exp_f32_e32 v54, v52
	v_or_b32_e32 v52, 2, v44
	v_ashrrev_i32_e32 v53, 31, v52
	v_mul_f32_e32 v45, 0x3d800000, v45
	v_add_f32_e32 v54, 1.0, v54
	v_log_f32_e32 v54, v54
	v_lshlrev_b64 v[52:53], 9, v[52:53]
	v_cvt_pk_bf16_f32 v45, v45, s0
	v_lshl_add_u64 v[60:61], v[42:43], 0, v[52:53]
	global_store_short v[60:61], v45, off
	v_min_f32_e32 v45, 0, v51
	v_fmac_f32_e32 v45, 0xbf317218, v54
	v_mfma_f32_16x16x32_bf16 v[52:55], v[34:37], v[22:25], 0
	v_mul_f32_e32 v45, 0x3d800000, v45
	v_lshlrev_b64 v[62:63], 9, v[62:63]
	v_cvt_pk_bf16_f32 v45, v45, s0
	v_mfma_f32_16x16x32_bf16 v[52:55], v[38:41], v[18:21], v[52:55]
	v_lshl_add_u64 v[62:63], v[42:43], 0, v[62:63]
	global_store_short v[62:63], v45, off
	s_waitcnt vmcnt(6)
	s_nop 4
	v_add_f32_e32 v51, v48, v52
	v_mul_f32_e64 v52, |v51|, s0
	v_exp_f32_e32 v52, v52
	v_min_f32_e32 v51, 0, v51
	v_add_f32_e32 v64, v48, v55
	v_add_f32_e32 v45, 1.0, v52
	v_add_f32_e32 v52, v48, v53
	v_log_f32_e32 v45, v45
	v_mul_f32_e64 v53, |v52|, s0
	v_exp_f32_e32 v53, v53
	v_fmac_f32_e32 v51, 0xbf317218, v45
	v_mul_f32_e32 v45, 0x3d800000, v51
	v_add_f32_e32 v51, 1.0, v53
	v_log_f32_e32 v51, v51
	v_cvt_pk_bf16_f32 v45, v45, s0
	global_store_short v[56:57], v45, off offset:32
	v_min_f32_e32 v45, 0, v52
	v_fmac_f32_e32 v45, 0xbf317218, v51
	v_add_f32_e32 v51, v48, v54
	v_mul_f32_e64 v52, |v51|, s0
	v_exp_f32_e32 v52, v52
	v_mul_f32_e32 v45, 0x3d800000, v45
	v_cvt_pk_bf16_f32 v45, v45, s0
	global_store_short v[58:59], v45, off offset:32
	v_min_f32_e32 v45, 0, v51
	v_add_f32_e32 v51, 1.0, v52
	v_mul_f32_e64 v52, |v64|, s0
	v_log_f32_e32 v51, v51
	v_exp_f32_e32 v52, v52
	v_fmac_f32_e32 v45, 0xbf317218, v51
	v_add_f32_e32 v51, 1.0, v52
	v_mfma_f32_16x16x32_bf16 v[52:55], v[34:37], v[14:17], 0
	v_log_f32_e32 v51, v51
	v_mul_f32_e32 v45, 0x3d800000, v45
	v_cvt_pk_bf16_f32 v45, v45, s0
	v_mfma_f32_16x16x32_bf16 v[52:55], v[38:41], v[10:13], v[52:55]
	global_store_short v[60:61], v45, off offset:32
	v_min_f32_e32 v45, 0, v64
	v_fmac_f32_e32 v45, 0xbf317218, v51
	v_mul_f32_e32 v45, 0x3d800000, v45
	v_cvt_pk_bf16_f32 v45, v45, s0
	s_waitcnt vmcnt(8)
	s_nop 1
	v_add_f32_e32 v51, v47, v52
	v_mul_f32_e64 v52, |v51|, s0
	v_exp_f32_e32 v52, v52
	global_store_short v[62:63], v45, off offset:32
	v_min_f32_e32 v51, 0, v51
	v_mfma_f32_16x16x32_bf16 v[34:37], v[34:37], v[6:9], 0
	v_add_f32_e32 v45, 1.0, v52
	v_add_f32_e32 v52, v47, v53
	v_log_f32_e32 v45, v45
	v_mul_f32_e64 v53, |v52|, s0
	v_exp_f32_e32 v53, v53
	v_mfma_f32_16x16x32_bf16 v[34:37], v[38:41], v[2:5], v[34:37]
	v_fmac_f32_e32 v51, 0xbf317218, v45
	v_mul_f32_e32 v45, 0x3d800000, v51
	v_add_f32_e32 v51, 1.0, v53
	v_log_f32_e32 v51, v51
	v_cvt_pk_bf16_f32 v45, v45, s0
	global_store_short v[56:57], v45, off offset:64
	v_min_f32_e32 v45, 0, v52
	v_fmac_f32_e32 v45, 0xbf317218, v51
	v_add_f32_e32 v51, v47, v54
	v_mul_f32_e64 v52, |v51|, s0
	v_exp_f32_e32 v52, v52
	v_mul_f32_e32 v45, 0x3d800000, v45
	v_cvt_pk_bf16_f32 v45, v45, s0
	global_store_short v[58:59], v45, off offset:64
	v_min_f32_e32 v45, 0, v51
	v_add_f32_e32 v51, 1.0, v52
	v_add_f32_e32 v52, v47, v55
	v_mul_f32_e64 v53, |v52|, s0
	v_log_f32_e32 v51, v51
	v_exp_f32_e32 v53, v53
	s_waitcnt vmcnt(10)
	v_add_f32_e32 v34, v46, v34
	v_mul_f32_e64 v38, |v34|, s0
	v_fmac_f32_e32 v45, 0xbf317218, v51
	v_add_f32_e32 v51, 1.0, v53
	v_log_f32_e32 v51, v51
	v_mul_f32_e32 v45, 0x3d800000, v45
	v_cvt_pk_bf16_f32 v45, v45, s0
	v_exp_f32_e32 v38, v38
	global_store_short v[60:61], v45, off offset:64
	v_min_f32_e32 v45, 0, v52
	v_fmac_f32_e32 v45, 0xbf317218, v51
	v_mul_f32_e32 v39, 0x3d800000, v45
	v_cvt_pk_bf16_f32 v39, v39, s0
	v_add_f32_e32 v38, 1.0, v38
	v_add_f32_e32 v35, v46, v35
	global_store_short v[62:63], v39, off offset:64
	v_log_f32_e32 v38, v38
	v_mul_f32_e64 v39, |v35|, s0
	v_exp_f32_e32 v39, v39
	v_min_f32_e32 v34, 0, v34
	v_fmac_f32_e32 v34, 0xbf317218, v38
	v_mul_f32_e32 v34, 0x3d800000, v34
	v_add_f32_e32 v38, 1.0, v39
	v_log_f32_e32 v38, v38
	v_cvt_pk_bf16_f32 v34, v34, s0
	global_store_short v[56:57], v34, off offset:96
	v_min_f32_e32 v34, 0, v35
	v_add_f32_e32 v35, v46, v36
	v_mul_f32_e64 v36, |v35|, s0
	v_exp_f32_e32 v36, v36
	v_fmac_f32_e32 v34, 0xbf317218, v38
	v_mul_f32_e32 v34, 0x3d800000, v34
	v_cvt_pk_bf16_f32 v34, v34, s0
	global_store_short v[58:59], v34, off offset:96
	v_add_f32_e32 v34, 1.0, v36
	v_add_f32_e32 v36, v46, v37
	v_log_f32_e32 v34, v34
	v_mul_f32_e64 v37, |v36|, s0
	v_exp_f32_e32 v37, v37
	v_min_f32_e32 v35, 0, v35
	v_fmac_f32_e32 v35, 0xbf317218, v34
	v_mul_f32_e32 v34, 0x3d800000, v35
	v_add_f32_e32 v35, 1.0, v37
	v_log_f32_e32 v35, v35
	v_cvt_pk_bf16_f32 v34, v34, s0
	global_store_short v[60:61], v34, off offset:96
	v_min_f32_e32 v34, 0, v36
	ds_read_b128 v[38:41], v50 offset:51200
	v_fmac_f32_e32 v34, 0xbf317218, v35
	v_mul_f32_e32 v45, 0x3d800000, v34
	ds_read_b128 v[34:37], v50 offset:51216
	v_cvt_pk_bf16_f32 v45, v45, s0
	global_store_short v[62:63], v45, off offset:96
	s_waitcnt lgkmcnt(1)
; #define LAS __attribute__((address_space(3)))
; __device__ __forceinline__ unsigned f2bf(float f) { return pk2(f, 0.f) & 0xffffu; }
; #define MFMA16(a, b, c) __builtin_amdgcn_mfma_f32_16x16x32_bf16((a), (b), (c), 0, 0, 0)
; __device__ __forceinline__ void gate_half_item(LAS unsigned char* lds, int tb, const bf16* H, const bf16* Win_t, bf16* GT, float* DTt, float* At, const float* bg_f, const float* bg_b, ...
;     ...
;                 for (int rt = 0; rt < 2; ++rt) { bf16x8 A1, A2;
;                     { const LAS f32x4* lp = (const LAS f32x4*)(LR + (16 * rt + lr_g) * 32 + 16 * d + ((8 * lq_g) & 15)); const f32x4 l0 = lp[0], l1 = lp[1]; const float lv[8] = {l0.x, l0.y, l0.z, l0.w, l1.x, l1.y, l1.z, l1.w};
; #pragma unroll
;                       for (int e = 0; e < 8; ++e) { const unsigned hi = f2bf(lv[e]); const float rem = lv[e] - __builtin_bit_cast(float, hi << 16);
;                           A1[e] = (lq_g < 2) ? (short)hi : (short)f2bf(rem); A2[e] = (lq_g < 2) ? (short)hi : (short)0; } }
; #pragma unroll
;                     for (int c4 = 0; c4 < 4; ++c4) { pg8::f32x4 acc = {0.f, 0.f, 0.f, 0.f}; acc = MFMA16(A1, B1[c4], acc); acc = MFMA16(A2, B2[c4], acc);
;                         const int colc = 16 * (4 * (wave & 3) + c4) + lr_g;
; #pragma unroll
;                         for (int r = 0; r < 4; ++r) { const float dot = acc[r] + bgc[c4];
;                             Gd[(size_t)(tb + 16 * rt + 4 * lq_g + r) * 256 + colc] = (bf16)f2bf((fminf(dot, 0.f) - 0.69314718056f * __builtin_amdgcn_logf(1.0f + __builtin_amdgcn_exp2f(-1.44269504089f * fabsf(dot)))) * (1.0f / 16.0f)); } } }
;                 { const int tok = tid >> 4, dh = tid & 15, dd = dh >> 3, hh = dh & 7; const size_t m = tb + tok;
;                     const float raw = DTR[tok * 16 + dh] + (dd ? dt_bias_b : dt_bias_f)[hh]; const float dt = fmaxf(raw, 0.f) + 0.69314718056f * __builtin_amdgcn_logf(1.0f + __builtin_amdgcn_exp2f(-1.44269504089f * fabsf(raw)));
	v_cvt_pk_bf16_f32 v45, v38, 0
	v_and_b32_e32 v50, 0xffff, v45
	s_and_saveexec_b64 s[0:1], s[4:5]
	v_lshlrev_b32_e32 v50, 16, v50
	v_sub_f32_e32 v38, v38, v50
	v_cvt_pk_bf16_f32 v50, v38, 0
	s_or_b64 exec, exec, s[0:1]
	v_cvt_pk_bf16_f32 v51, v39, 0
	v_and_b32_e32 v38, 0xffff, v51
	s_and_saveexec_b64 s[0:1], s[4:5]
	v_lshlrev_b32_e32 v38, 16, v38
	v_sub_f32_e32 v38, v39, v38
	v_cvt_pk_bf16_f32 v38, v38, 0
	s_or_b64 exec, exec, s[0:1]
	v_cvt_pk_bf16_f32 v52, v40, 0
	v_and_b32_e32 v39, 0xffff, v52
	s_and_saveexec_b64 s[0:1], s[4:5]
	v_lshlrev_b32_e32 v39, 16, v39
	v_sub_f32_e32 v39, v40, v39
	v_cvt_pk_bf16_f32 v39, v39, 0
	s_or_b64 exec, exec, s[0:1]
	v_cvt_pk_bf16_f32 v53, v41, 0
	v_and_b32_e32 v40, 0xffff, v53
	s_and_saveexec_b64 s[0:1], s[4:5]
	v_lshlrev_b32_e32 v40, 16, v40
	v_sub_f32_e32 v40, v41, v40
	v_cvt_pk_bf16_f32 v40, v40, 0
	s_or_b64 exec, exec, s[0:1]
	s_waitcnt lgkmcnt(0)
	v_cvt_pk_bf16_f32 v54, v34, 0
	v_and_b32_e32 v41, 0xffff, v54
	s_and_saveexec_b64 s[0:1], s[4:5]
	v_lshlrev_b32_e32 v41, 16, v41
	v_sub_f32_e32 v34, v34, v41
	v_cvt_pk_bf16_f32 v41, v34, 0
	s_or_b64 exec, exec, s[0:1]
	v_cvt_pk_bf16_f32 v56, v35, 0
	v_and_b32_e32 v34, 0xffff, v56
	s_and_saveexec_b64 s[0:1], s[4:5]
	v_lshlrev_b32_e32 v34, 16, v34
	v_sub_f32_e32 v34, v35, v34
	v_cvt_pk_bf16_f32 v34, v34, 0
	s_or_b64 exec, exec, s[0:1]
	v_cvt_pk_bf16_f32 v57, v36, 0
	v_and_b32_e32 v35, 0xffff, v57
	s_and_saveexec_b64 s[0:1], s[4:5]
	v_lshlrev_b32_e32 v35, 16, v35
	v_sub_f32_e32 v35, v36, v35
	v_cvt_pk_bf16_f32 v35, v35, 0
	s_or_b64 exec, exec, s[0:1]
	v_cvt_pk_bf16_f32 v55, v37, 0
	s_mov_b32 s3, 0x5040100
	v_and_b32_e32 v36, 0xffff, v55
	v_perm_b32 v52, v52, v51, s3
	v_perm_b32 v53, v54, v53, s3
	v_perm_b32 v51, v57, v56, s3
	s_and_saveexec_b64 s[0:1], s[4:5]
	v_lshlrev_b32_e32 v36, 16, v36
	v_sub_f32_e32 v36, v37, v36
	v_mov_b32_e32 v45, 0
	v_cvt_pk_bf16_f32 v36, v36, 0
	v_mov_b32_e32 v52, 0
	v_mov_b32_e32 v53, 0
	v_mov_b32_e32 v51, 0
	s_or_b64 exec, exec, s[0:1]
	v_perm_b32 v37, v36, v35, s3
	v_perm_b32 v36, v34, v41, s3
	v_perm_b32 v35, v40, v39, s3
	v_perm_b32 v34, v38, v50, s3
	v_cndmask_b32_e32 v41, 0, v55, vcc
	v_perm_b32 v38, v52, v45, s3
	v_alignbit_b32 v39, v53, v52, 16
	v_alignbit_b32 v40, v51, v53, 16
	v_alignbit_b32 v41, v41, v51, 16
	v_mfma_f32_16x16x32_bf16 v[30:33], v[34:37], v[30:33], 0
	s_mov_b32 s0, 0xbfb8aa3b
	v_or_b32_e32 v50, 16, v44
	v_ashrrev_i32_e32 v51, 31, v50
	v_mfma_f32_16x16x32_bf16 v[26:29], v[38:41], v[26:29], v[30:33]
	v_bfe_u32 v53, v1, 3, 1
	v_cmp_eq_u32_e32 vcc, 0, v53
	v_lshlrev_b32_e32 v54, 2, v1
	v_mfma_f32_16x16x32_bf16 v[22:25], v[34:37], v[22:25], 0
	v_ashrrev_i32_e32 v1, 4, v1
	s_nop 2
	v_add_f32_e32 v26, v49, v26
	v_mul_f32_e64 v30, |v26|, s0
	v_exp_f32_e32 v32, v30
	v_add_f32_e32 v33, v49, v27
	v_min_f32_e32 v26, 0, v26
	v_lshlrev_b64 v[30:31], 9, v[50:51]
	v_add_f32_e32 v27, 1.0, v32
	v_log_f32_e32 v27, v27
	v_mul_f32_e64 v32, |v33|, s0
	v_exp_f32_e32 v32, v32
	v_add_f32_e32 v28, v49, v28
	v_fmac_f32_e32 v26, 0xbf317218, v27
	v_mul_f32_e32 v26, 0x3d800000, v26
	v_cvt_pk_bf16_f32 v45, v26, s0
	v_add_f32_e32 v26, 1.0, v32
	v_log_f32_e32 v32, v26
	v_lshl_add_u64 v[26:27], v[42:43], 0, v[30:31]
	v_min_f32_e32 v30, 0, v33
	global_store_short v[26:27], v45, off
	v_fmac_f32_e32 v30, 0xbf317218, v32
	v_mul_f32_e32 v30, 0x3d800000, v30
	v_cvt_pk_bf16_f32 v45, v30, s0
	v_mul_f32_e64 v30, |v28|, s0
	v_exp_f32_e32 v32, v30
	v_mov_b32_e32 v33, s45
	v_mov_b32_e32 v50, s44
	v_mov_b32_e32 v51, 0
	v_add_f32_e32 v52, 1.0, v32
	v_mov_b32_e32 v32, s47
	v_cndmask_b32_e32 v33, v32, v33, vcc
	v_mov_b32_e32 v32, s46
	v_cndmask_b32_e32 v32, v32, v50, vcc
	v_and_b32_e32 v50, 28, v54
	v_lshl_add_u64 v[32:33], v[32:33], 0, v[50:51]
	global_load_dword v55, v[32:33], off
	v_mfma_f32_16x16x32_bf16 v[18:21], v[38:41], v[18:21], v[22:25]
	v_log_f32_e32 v32, v52
	v_or_b32_e32 v30, 17, v44
	v_min_f32_e32 v28, 0, v28
	v_ashrrev_i32_e32 v31, 31, v30
	v_fmac_f32_e32 v28, 0xbf317218, v32
	s_nop 2
	v_add_f32_e32 v18, v48, v18
	v_mul_f32_e64 v22, |v18|, s0
	v_exp_f32_e32 v24, v22
	v_add_f32_e32 v19, v48, v19
	v_mul_f32_e64 v25, |v19|, s0
	v_exp_f32_e32 v25, v25
	v_add_f32_e32 v24, 1.0, v24
	v_log_f32_e32 v24, v24
	v_min_f32_e32 v18, 0, v18
	v_lshlrev_b64 v[30:31], 9, v[30:31]
	v_mul_f32_e32 v28, 0x3d800000, v28
	v_fmac_f32_e32 v18, 0xbf317218, v24
	v_mul_f32_e32 v18, 0x3d800000, v18
	v_add_f32_e32 v24, 1.0, v25
	v_log_f32_e32 v24, v24
	v_cvt_pk_bf16_f32 v18, v18, s0
	global_store_short v[26:27], v18, off offset:32
	v_min_f32_e32 v18, 0, v19
	v_add_f32_e32 v19, v48, v20
	v_mul_f32_e64 v20, |v19|, s0
	v_exp_f32_e32 v20, v20
	v_add_f32_e32 v33, v49, v29
	v_fmac_f32_e32 v18, 0xbf317218, v24
	v_lshl_add_u64 v[30:31], v[42:43], 0, v[30:31]
	v_cvt_pk_bf16_f32 v32, v28, s0
	v_mul_f32_e64 v28, |v33|, s0
	v_mul_f32_e32 v18, 0x3d800000, v18
	global_store_short v[30:31], v45, off
	v_exp_f32_e32 v45, v28
	v_cvt_pk_bf16_f32 v18, v18, s0
	global_store_short v[30:31], v18, off offset:32
	v_add_f32_e32 v18, 1.0, v20
	v_add_f32_e32 v20, v48, v21
	v_log_f32_e32 v18, v18
	v_mul_f32_e64 v21, |v20|, s0
	v_exp_f32_e32 v21, v21
	v_or_b32_e32 v28, 18, v44
	v_add_f32_e32 v45, 1.0, v45
	v_ashrrev_i32_e32 v29, 31, v28
	v_log_f32_e32 v45, v45
	v_min_f32_e32 v19, 0, v19
	v_lshlrev_b64 v[28:29], 9, v[28:29]
	v_fmac_f32_e32 v19, 0xbf317218, v18
	v_lshl_add_u64 v[28:29], v[42:43], 0, v[28:29]
	v_mul_f32_e32 v18, 0x3d800000, v19
	v_add_f32_e32 v19, 1.0, v21
	global_store_short v[28:29], v32, off
	v_min_f32_e32 v32, 0, v33
	v_log_f32_e32 v19, v19
	v_fmac_f32_e32 v32, 0xbf317218, v45
	v_mul_f32_e32 v32, 0x3d800000, v32
	v_cvt_pk_bf16_f32 v18, v18, s0
	v_cvt_pk_bf16_f32 v45, v32, s0
	v_or_b32_e32 v32, 19, v44
	global_store_short v[28:29], v18, off offset:32
	v_min_f32_e32 v18, 0, v20
	v_ashrrev_i32_e32 v33, 31, v32
	v_fmac_f32_e32 v18, 0xbf317218, v19
	v_lshlrev_b64 v[22:23], 9, v[32:33]
	v_mul_f32_e32 v18, 0x3d800000, v18
	v_lshl_add_u64 v[22:23], v[42:43], 0, v[22:23]
	v_cvt_pk_bf16_f32 v18, v18, s0
	global_store_short v[22:23], v18, off offset:32
	v_add_u32_e32 v18, 0, v54
	ds_read_b32 v18, v18 offset:53248
	v_mfma_f32_16x16x32_bf16 v[14:17], v[34:37], v[14:17], 0
	v_mov_b32_e32 v19, s40
	global_store_short v[22:23], v45, off
	v_mfma_f32_16x16x32_bf16 v[10:13], v[38:41], v[10:13], v[14:17]
	v_mfma_f32_16x16x32_bf16 v[6:9], v[34:37], v[6:9], 0
	s_waitcnt vmcnt(7) lgkmcnt(0)
; __device__ __forceinline__ unsigned f2bf(float f) { return pk2(f, 0.f) & 0xffffu; }
; __device__ __forceinline__ void xcd_barrier(const XcdBarrier& b) {
;     asm volatile("s_waitcnt vmcnt(0)" ::: "memory");
;     __syncthreads();
;     if (threadIdx.x == 0) {
;         unsigned* bar = b.bar;
;         __builtin_amdgcn_s_waitcnt(0);
;         unsigned nloc = b.st[0], nx = b.st[1];
;         if (nloc == 0u) { xcd_barrier_complete(bar, b.x, nloc, nx); b.st[0] = nloc; b.st[1] = nx; }
; __device__ __forceinline__ void gate_half_item(LAS unsigned char* lds, int tb, const bf16* H, const bf16* Win_t, bf16* GT, float* DTt, float* At, const float* bg_f, const float* bg_b, ...
;     ...
;                         for (int r = 0; r < 4; ++r) { const float dot = acc[r] + bgc[c4];
;                             Gd[(size_t)(tb + 16 * rt + 4 * lq_g + r) * 256 + colc] = (bf16)f2bf((fminf(dot, 0.f) - 0.69314718056f * __builtin_amdgcn_logf(1.0f + __builtin_amdgcn_exp2f(-1.44269504089f * fabsf(dot)))) * (1.0f / 16.0f)); } } }
;                 { const int tok = tid >> 4, dh = tid & 15, dd = dh >> 3, hh = dh & 7; const size_t m = tb + tok;
;                     const float raw = DTR[tok * 16 + dh] + (dd ? dt_bias_b : dt_bias_f)[hh]; const float dt = fmaxf(raw, 0.f) + 0.69314718056f * __builtin_amdgcn_logf(1.0f + __builtin_amdgcn_exp2f(-1.44269504089f * fabsf(raw)));
;                     DTt[((size_t)dd * MALL + m) * 8 + hh] = dt; At[((size_t)dd * MALL + m) * 8 + hh] = -dt * __expf((dd ? a_log_b : a_log_f)[hh]); }
;                 __syncthreads();
	s_nop 2
	v_add_f32_e32 v16, v18, v55
	v_mul_f32_e64 v14, |v16|, s0
	v_exp_f32_e32 v14, v14
	v_add_f32_e32 v10, v47, v10
	v_mul_f32_e64 v15, |v10|, s0
	v_exp_f32_e32 v18, v15
	v_add_f32_e32 v14, 1.0, v14
	v_log_f32_e32 v17, v14
	v_add_u32_e32 v14, s6, v1
	v_max_f32_e32 v1, 0, v16
	v_ashrrev_i32_e32 v15, 31, v14
	v_fmamk_f32 v1, v17, 0x3f317218, v1
	v_mul_u32_u24_e32 v16, 0x4400, v53
	v_mov_b32_e32 v17, v51
	v_lshl_add_u64 v[14:15], v[16:17], 0, v[14:15]
	v_lshlrev_b64 v[14:15], 5, v[14:15]
	v_or_b32_e32 v14, v14, v50
	v_lshl_add_u64 v[16:17], s[14:15], 0, v[14:15]
	global_store_dword v[16:17], v1, off
	v_mov_b32_e32 v16, s43
	v_mov_b32_e32 v17, s41
	v_cndmask_b32_e32 v17, v16, v17, vcc
	v_mov_b32_e32 v16, s42
	v_cndmask_b32_e32 v16, v16, v19, vcc
	v_lshl_add_u64 v[16:17], v[16:17], 0, v[50:51]
	global_load_dword v16, v[16:17], off
	v_add_f32_e32 v17, 1.0, v18
	v_add_f32_e32 v11, v47, v11
	v_log_f32_e32 v17, v17
	v_mul_f32_e64 v18, |v11|, s0
	v_exp_f32_e32 v18, v18
	v_min_f32_e32 v10, 0, v10
	v_fmac_f32_e32 v10, 0xbf317218, v17
	v_mul_f32_e32 v10, 0x3d800000, v10
	v_add_f32_e32 v17, 1.0, v18
	v_log_f32_e32 v17, v17
	v_cvt_pk_bf16_f32 v10, v10, s0
	global_store_short v[26:27], v10, off offset:64
	v_min_f32_e32 v10, 0, v11
	v_add_f32_e32 v11, v47, v12
	v_mul_f32_e64 v12, |v11|, s0
	v_exp_f32_e32 v12, v12
	v_fmac_f32_e32 v10, 0xbf317218, v17
	v_mul_f32_e32 v10, 0x3d800000, v10
	v_cvt_pk_bf16_f32 v10, v10, s0
	global_store_short v[30:31], v10, off offset:64
	v_min_f32_e32 v10, 0, v11
	v_add_f32_e32 v11, 1.0, v12
	v_add_f32_e32 v12, v47, v13
	v_mul_f32_e64 v13, |v12|, s0
	v_log_f32_e32 v11, v11
	v_exp_f32_e32 v13, v13
	v_mfma_f32_16x16x32_bf16 v[2:5], v[38:41], v[2:5], v[6:9]
	v_fmac_f32_e32 v10, 0xbf317218, v11
	v_add_f32_e32 v11, 1.0, v13
	v_log_f32_e32 v11, v11
	v_mul_f32_e32 v10, 0x3d800000, v10
	s_nop 3
	v_add_f32_e32 v2, v46, v2
	v_mul_f32_e64 v6, |v2|, s0
	v_cvt_pk_bf16_f32 v10, v10, s0
	v_exp_f32_e32 v6, v6
	global_store_short v[28:29], v10, off offset:64
	v_min_f32_e32 v10, 0, v12
	v_fmac_f32_e32 v10, 0xbf317218, v11
	v_mul_f32_e32 v7, 0x3d800000, v10
	v_cvt_pk_bf16_f32 v7, v7, s0
	v_add_f32_e32 v6, 1.0, v6
	v_add_f32_e32 v3, v46, v3
	global_store_short v[22:23], v7, off offset:64
	v_log_f32_e32 v6, v6
	v_mul_f32_e64 v7, |v3|, s0
	v_exp_f32_e32 v7, v7
	v_min_f32_e32 v2, 0, v2
	v_fmac_f32_e32 v2, 0xbf317218, v6
	v_mul_f32_e32 v2, 0x3d800000, v2
	v_add_f32_e32 v6, 1.0, v7
	v_log_f32_e32 v6, v6
	v_cvt_pk_bf16_f32 v2, v2, s0
	global_store_short v[26:27], v2, off offset:96
	v_min_f32_e32 v2, 0, v3
	v_add_f32_e32 v3, v46, v4
	v_mul_f32_e64 v4, |v3|, s0
	v_exp_f32_e32 v4, v4
	v_fmac_f32_e32 v2, 0xbf317218, v6
	v_mul_f32_e32 v2, 0x3d800000, v2
	v_cvt_pk_bf16_f32 v2, v2, s0
	global_store_short v[30:31], v2, off offset:96
	v_add_f32_e32 v2, 1.0, v4
	v_add_f32_e32 v4, v46, v5
	v_log_f32_e32 v2, v2
	v_mul_f32_e64 v5, |v4|, s0
	v_exp_f32_e32 v5, v5
	v_min_f32_e32 v3, 0, v3
	v_fmac_f32_e32 v3, 0xbf317218, v2
	v_mul_f32_e32 v2, 0x3d800000, v3
	v_add_f32_e32 v3, 1.0, v5
	v_log_f32_e32 v3, v3
	v_cvt_pk_bf16_f32 v2, v2, s0
	global_store_short v[28:29], v2, off offset:96
	v_min_f32_e32 v2, 0, v4
	v_fmac_f32_e32 v2, 0xbf317218, v3
	v_mul_f32_e32 v2, 0x3d800000, v2
	v_cvt_pk_bf16_f32 v2, v2, s0
	global_store_short v[22:23], v2, off offset:96
	s_waitcnt vmcnt(8)
	v_mul_f32_e32 v3, 0x3fb8aa3b, v16
	v_exp_f32_e32 v3, v3
	s_nop 0
	v_mul_f32_e64 v1, v3, -v1
	v_lshl_add_u64 v[2:3], s[22:23], 0, v[14:15]
	global_store_dword v[2:3], v1, off
	s_barrier
	s_waitcnt vmcnt(0)
	s_barrier
	s_mov_b64 s[4:5], exec
	v_readlane_b32 s0, v240, 8
	v_readlane_b32 s1, v240, 9
	s_and_b64 s[0:1], s[4:5], s[0:1]
	s_mov_b64 exec, s[0:1]
	s_cbranch_execz .LBB0_251
	s_add_i32 s0, 0, 0x20160
	v_mov_b32_e32 v1, s0
	s_waitcnt vmcnt(0) expcnt(0) lgkmcnt(0)
	ds_read_b32 v3, v1
	s_add_i32 s0, 0, 0x20164
	v_mov_b32_e32 v1, s0
	ds_read_b32 v1, v1
	s_waitcnt lgkmcnt(1)
	v_cmp_ne_u32_e32 vcc, 0, v3
	s_cbranch_vccnz .LBB0_215
	s_add_u32 s6, s78, 0x4200
	s_addc_u32 s7, s79, 0
	s_add_u32 s18, s78, 0x4400
	s_addc_u32 s19, s79, 0
	s_add_u32 s20, s78, 0x4500
	s_addc_u32 s21, s79, 0
	s_add_u32 s26, s78, 0x4600
	s_addc_u32 s27, s79, 0
	s_add_u32 s28, s78, 0x4700
	s_addc_u32 s29, s79, 0
	s_add_u32 s56, s78, 0x4800
	s_addc_u32 s57, s79, 0
	s_add_u32 s68, s78, 0x4900
	s_addc_u32 s69, s79, 0
	s_add_u32 s80, s78, 0x4a00
	s_addc_u32 s81, s79, 0
	s_add_u32 s82, s78, 0x4b00
	s_addc_u32 s83, s79, 0
	s_add_u32 s84, s78, 0x4c00
	s_addc_u32 s85, s79, 0
	s_add_u32 s86, s78, 0x4d00
	s_addc_u32 s87, s79, 0
	s_add_u32 s88, s78, 0x4e00
	s_addc_u32 s89, s79, 0
	s_add_u32 s90, s78, 0x4f00
	s_addc_u32 s91, s79, 0
	s_add_u32 s92, s78, 0x5000
	s_load_dwordx2 s[0:1], s[74:75], 0xf0
	s_load_dword s3, s[74:75], 0xf8
	s_addc_u32 s93, s79, 0
	s_add_u32 s94, s78, 0x5100
	s_addc_u32 s95, s79, 0
	s_add_u32 s12, s78, 0x5200
	s_waitcnt lgkmcnt(0)
	s_mul_i32 s0, s1, s0
	s_addc_u32 s13, s79, 0
	s_mul_i32 s3, s0, s3
	s_add_u32 s0, s78, 0x5300
	s_addc_u32 s1, s79, 0
	s_mov_b32 s74, 1
	v_mov_b32_e32 v17, 0
	s_branch .LBB0_203
